# attention per-unit overhead: next ticket fetched during epilogue, sub-LN gain loads issued before the hand-off barrier, first-tile alpha==1 multiplies skipped; P8 epilogue DPP old-value inits removed
# speedup vs baseline: 1.0105x; 1.0026x over previous
; #define LAS __attribute__((address_space(3)))
; #define INP(k) ((const float*)(GAS const float*)KARG64(8 * (k)))
; #define WSP() ((unsigned char*)(GAS unsigned char*)KARG64(240))
; __global__ void __launch_bounds__(NWAVES * 64, 2) hybrid_fwd(Params P) {
;     ...
;         const float gqm = fabsf(INP(14)[lane]), gkm = fabsf(INP(15)[lane]);
;         float gq = gqm, gk = gkm;
; #pragma unroll
;         for (int o = 1; o < 64; o <<= 1) { gq = fmaxf(gq, __shfl_xor(gq, o)); gk = fmaxf(gk, __shfl_xor(gk, o)); }
;         const float Rb = 2.2f * 8.f * gq * gk + 110.f;
;         volatile LAS int* qw = (volatile LAS int*)(lds + LDS_X + 512);
;         unsigned* qctr = (unsigned*)(WSP() + WS_BAR) + 4000;
;         const float lam = __expf(wave_sum(INP(16)[lane] * INP(17)[lane])) - __expf(wave_sum(INP(18)[lane] * INP(19)[lane])) + 0.2f;
;         for (;;) {
;             if (tid == 0) *qw = (int)atomicAdd(qctr, 1u);
.LBB0_554:
	s_mov_b64 s[4:5], s[0:1]
	s_load_dwordx2 s[4:5], s[4:5], 0x70
	v_lshlrev_b32_e32 v1, 2, v174
	s_mov_b64 s[6:7], s[0:1]
	s_mov_b64 s[8:9], s[0:1]
	v_mbcnt_lo_u32_b32 v9, -1, 0
	s_waitcnt lgkmcnt(0)
	global_load_dword v2, v1, s[4:5]
	s_load_dwordx2 s[4:5], s[6:7], 0x78
	s_mov_b64 s[6:7], s[0:1]
	v_mbcnt_hi_u32_b32 v9, -1, v9
	v_and_b32_e32 v10, 64, v9
	v_xor_b32_e32 v11, 1, v9
	s_waitcnt lgkmcnt(0)
	global_load_dword v3, v1, s[4:5]
	s_load_dwordx2 s[4:5], s[6:7], 0xf0
	s_load_dwordx2 s[6:7], s[8:9], 0x80
	s_mov_b64 s[8:9], s[0:1]
	v_add_u32_e32 v10, 64, v10
	v_xor_b32_e32 v12, 2, v9
	v_cmp_lt_i32_e32 vcc, v11, v10
	s_waitcnt lgkmcnt(0)
	global_load_dword v4, v1, s[6:7]
	s_load_dwordx2 s[6:7], s[8:9], 0x88
	s_mov_b64 s[8:9], s[0:1]
	v_xor_b32_e32 v13, 4, v9
	v_cndmask_b32_e32 v11, v9, v11, vcc
	v_cmp_lt_i32_e32 vcc, v12, v10
	s_waitcnt lgkmcnt(0)
	global_load_dword v6, v1, s[6:7]
	s_load_dwordx2 s[6:7], s[8:9], 0x90
	s_mov_b64 s[8:9], s[0:1]
	v_xor_b32_e32 v14, 8, v9
	v_cndmask_b32_e32 v12, v9, v12, vcc
	v_cmp_lt_i32_e32 vcc, v13, v10
	s_waitcnt lgkmcnt(0)
	global_load_dword v7, v1, s[6:7]
	s_load_dwordx2 s[6:7], s[8:9], 0x98
	v_xor_b32_e32 v15, 16, v9
	v_cndmask_b32_e32 v13, v9, v13, vcc
	v_cmp_lt_i32_e32 vcc, v14, v10
	v_xor_b32_e32 v16, 32, v9
	s_waitcnt lgkmcnt(0)
	global_load_dword v8, v1, s[6:7]
	v_cndmask_b32_e32 v14, v9, v14, vcc
	v_cmp_lt_i32_e32 vcc, v15, v10
	s_add_u32 s4, s4, 0x83e80
	s_addc_u32 s5, s5, 0
	v_cndmask_b32_e32 v15, v9, v15, vcc
	v_cmp_lt_i32_e32 vcc, v16, v10
	v_lshlrev_b32_e32 v10, 2, v11
	v_lshlrev_b32_e32 v11, 2, v12
	v_lshlrev_b32_e32 v12, 2, v13
	v_lshlrev_b32_e32 v13, 2, v14
	v_lshlrev_b32_e32 v14, 2, v15
	v_cndmask_b32_e32 v9, v9, v16, vcc
	v_lshlrev_b32_e32 v9, 2, v9
	s_add_i32 s33, 0, 0x20200
	s_mov_b32 s83, 0
	v_mov_b32_e32 v5, 0
	s_movk_i32 s76, 0x2400
	s_mov_b32 s77, 0x7ffffc
	s_mov_b64 s[84:85], 0x10000
	v_mov_b32_e32 v1, 0x358637bd
	v_mov_b32_e32 v175, 0x46000000
	v_mov_b32_e32 v188, 0x404000
	v_mov_b32_e32 v189, 0x4800
	v_mov_b32_e32 v190, 0xf149f2ca
	v_writelane_b32 v240, s4, 12
	v_mov_b32_e32 v191, s33
	v_mov_b32_e32 v193, 0x8000
	v_writelane_b32 v240, s5, 13
	s_waitcnt vmcnt(0)
	v_and_b32_e32 v15, 0x7fffffff, v2
	ds_bpermute_b32 v15, v10, v15
	v_max_f32_e64 v2, |v2|, |v2|
	s_waitcnt lgkmcnt(0)
	v_max_f32_e32 v15, v15, v15
	v_and_b32_e32 v16, 0x7fffffff, v3
	ds_bpermute_b32 v16, v10, v16
	v_max_f32_e32 v2, v2, v15
	ds_bpermute_b32 v15, v11, v2
	v_max_f32_e64 v3, |v3|, |v3|
	s_waitcnt lgkmcnt(1)
	v_max_f32_e32 v16, v16, v16
	v_max_f32_e32 v3, v3, v16
	s_waitcnt lgkmcnt(0)
	v_max_f32_e32 v15, v15, v15
	ds_bpermute_b32 v16, v11, v3
	v_max_f32_e32 v2, v2, v15
	ds_bpermute_b32 v15, v12, v2
	s_waitcnt lgkmcnt(1)
	v_max_f32_e32 v16, v16, v16
	v_max_f32_e32 v3, v3, v16
	v_mul_f32_e32 v17, v4, v6
	s_waitcnt lgkmcnt(0)
	v_max_f32_e32 v15, v15, v15
	ds_bpermute_b32 v16, v10, v17
	ds_bpermute_b32 v17, v12, v3
	v_max_f32_e32 v2, v2, v15
	ds_bpermute_b32 v15, v13, v2
	s_waitcnt lgkmcnt(2)
	v_fmac_f32_e32 v16, v4, v6
	s_waitcnt lgkmcnt(1)
	v_max_f32_e32 v4, v17, v17
	v_max_f32_e32 v3, v3, v4
	s_waitcnt lgkmcnt(0)
	v_max_f32_e32 v4, v15, v15
	ds_bpermute_b32 v6, v11, v16
	v_max_f32_e32 v2, v2, v4
	ds_bpermute_b32 v4, v13, v3
	v_mul_f32_e32 v15, v7, v8
	ds_bpermute_b32 v10, v10, v15
	ds_bpermute_b32 v15, v14, v2
	s_waitcnt lgkmcnt(3)
	v_add_f32_e32 v6, v16, v6
	ds_bpermute_b32 v16, v12, v6
	s_waitcnt lgkmcnt(3)
	v_max_f32_e32 v4, v4, v4
	s_waitcnt lgkmcnt(2)
	v_fmac_f32_e32 v10, v7, v8
	ds_bpermute_b32 v7, v11, v10
	v_max_f32_e32 v3, v3, v4
	s_waitcnt lgkmcnt(2)
	v_max_f32_e32 v4, v15, v15
	v_max_f32_e32 v2, v2, v4
	ds_bpermute_b32 v4, v14, v3
	s_waitcnt lgkmcnt(1)
	v_add_f32_e32 v7, v10, v7
	ds_bpermute_b32 v8, v12, v7
	v_add_f32_e32 v6, v6, v16
	ds_bpermute_b32 v11, v13, v6
	s_waitcnt lgkmcnt(2)
	v_max_f32_e32 v4, v4, v4
	v_max_f32_e32 v3, v3, v4
	s_waitcnt lgkmcnt(1)
	v_add_f32_e32 v7, v7, v8
	ds_bpermute_b32 v8, v13, v7
	s_waitcnt lgkmcnt(1)
	v_add_f32_e32 v4, v6, v11
	ds_bpermute_b32 v6, v14, v4
	ds_bpermute_b32 v10, v9, v2
	s_waitcnt lgkmcnt(2)
	v_add_f32_e32 v7, v7, v8
	ds_bpermute_b32 v8, v14, v7
	s_waitcnt lgkmcnt(2)
	v_add_f32_e32 v4, v4, v6
	ds_bpermute_b32 v6, v9, v4
	s_waitcnt lgkmcnt(2)
	v_max_f32_e32 v10, v10, v10
	v_max_f32_e32 v2, v2, v10
	s_waitcnt lgkmcnt(1)
	v_add_f32_e32 v7, v7, v8
	ds_bpermute_b32 v8, v9, v7
	ds_bpermute_b32 v10, v9, v3
	s_waitcnt lgkmcnt(2)
	v_add_f32_e32 v4, v4, v6
	v_mul_f32_e32 v4, 0x3fb8aa3b, v4
	v_exp_f32_e32 v4, v4
	s_waitcnt lgkmcnt(1)
	v_add_f32_e32 v6, v7, v8
	v_mul_f32_e32 v6, 0x3fb8aa3b, v6
	v_exp_f32_e32 v6, v6
	s_waitcnt lgkmcnt(0)
	v_max_f32_e32 v7, v10, v10
	v_mul_f32_e32 v2, 0x418ccccd, v2
	v_max_f32_e32 v3, v3, v7
	v_fmaak_f32 v192, v3, v2, 0x42dc0000
	v_sub_f32_e32 v2, v4, v6
	v_add_f32_e32 v176, 0x3e4ccccd, v2
	v_mov_b32_e32 v177, v176
	v_readlane_b32 s98, v240, 3
	s_nop 3
	s_cmp_lg_u32 s98, 0
	s_cbranch_scc1 .Latk_a
	v_readlane_b32 s100, v240, 12
	v_readlane_b32 s101, v240, 13
	s_mov_b64 s[98:99], exec
	s_mov_b64 exec, 1
	v_mov_b32_e32 v244, 1
	v_mov_b32_e32 v245, 0
	s_nop 4
	global_atomic_add v244, v245, v244, s[100:101] sc0
	s_mov_b64 exec, s[98:99]
.Latk_a:
	s_branch .LBB0_558

; __global__ void __launch_bounds__(NWAVES * 64, 2) hybrid_fwd(Params P) {
;     ...
;         for (;;) {
;             if (tid == 0) *qw = (int)atomicAdd(qctr, 1u);
;             __syncthreads();
;             const int id = *qw;
;             __syncthreads();
;             if (id >= 1024 + 4) break;
.LBB0_558:
	s_mov_b64 s[4:5], exec
	v_readlane_b32 s6, v240, 1
	v_readlane_b32 s7, v240, 2
	s_and_b64 s[6:7], s[4:5], s[6:7]
	s_mov_b64 exec, s[6:7]
	s_cbranch_execz .LBB0_562
	s_mov_b64 s[8:9], exec
	v_mbcnt_lo_u32_b32 v2, s8, 0
	v_mbcnt_hi_u32_b32 v2, s9, v2
	v_cmp_eq_u32_e32 vcc, 0, v2
	s_and_saveexec_b64 s[6:7], vcc
	s_cbranch_execz .LBB0_561
	s_bcnt1_i32_b64 s8, s[8:9]
	v_mov_b32_e32 v3, s8
	v_readlane_b32 s8, v240, 12
	v_readlane_b32 s9, v240, 13
	s_nop 4
	s_waitcnt vmcnt(0)
	v_mov_b32_e32 v3, v244

; __device__ __forceinline__ void attn_unit(const bf16* __restrict__ QB, const bf16* __restrict__ KB, const bf16* __restrict__ VB, bf16* __restrict__ YATT, ...
;     ...
;             float mx = fmaxf(s0[0], s1[0]);
; #pragma unroll
;             for (int r = 1; r < 16; ++r) mx = fmaxf(mx, fmaxf(s0[r], s1[r]));
;             { auto rr = __builtin_amdgcn_permlane32_swap(__float_as_uint(mx), __float_as_uint(mx), false, false); mx = fmaxf(__uint_as_float(rr[0]), __uint_as_float(rr[1])); }
;             const bool need = (j == jsw) || (mx > THR);
;             if (__any(need)) {
;                 const float delta = need ? mx : 0.f;
;                 const float alpha = (j == jsw) ? 1.f : __builtin_amdgcn_exp2f(-delta);
;                 lrun *= alpha;
; #pragma unroll
;                 for (int r = 0; r < 16; ++r) { s0[r] -= delta; s1[r] -= delta; negc[r] -= delta; }
; #pragma unroll
;                 for (int e = 0; e < 4; ++e)
; #pragma unroll
;                     for (int r = 0; r < 16; ++r) acc[e][r] *= alpha;
;             }
.LBB0_577:
	s_or_b64 exec, exec, s[78:79]
	s_nop 8
	v_max3_f32 v2, v98, v99, v100
	v_max3_f32 v3, v101, v102, v103
	v_max3_f32 v4, v104, v105, v106
	v_max3_f32 v6, v107, v108, v109
	v_max3_f32 v2, v2, v110, v111
	v_max3_f32 v3, v3, v112, v113
	v_max3_f32 v4, v4, v114, v115
	v_max3_f32 v6, v6, v116, v117
	v_max3_f32 v2, v2, v118, v119
	v_max3_f32 v3, v3, v120, v121
	v_max3_f32 v4, v4, v122, v123
	v_max3_f32 v6, v6, v124, v125
	v_max3_f32 v2, v2, v126, v127
	v_max3_f32 v3, v3, v128, v129
	v_max3_f32 v2, v2, v3, v4
	v_max_f32_e32 v2, v2, v6
	v_mov_b32_e32 v3, v2
	s_nop 1
	v_permlane32_swap_b32_e32 v2, v3
	v_max_f32_e32 v3, v3, v3
	v_max_f32_e32 v2, v2, v2
	v_max_f32_e32 v2, v2, v3
	s_mov_b32 s10, 0x42700000
	v_cmp_eq_u32_e64 s[8:9], s81, v206
	v_cmp_lt_f32_e32 vcc, s10, v2
	s_or_b64 vcc, s[8:9], vcc
	s_cbranch_vccz .LBB0_579
	v_cndmask_b32_e32 v2, 0, v2, vcc
	v_exp_f32_e64 v3, -v2
	v_sub_f32_e32 v97, v97, v2
	v_sub_f32_e32 v96, v96, v2
	v_sub_f32_e32 v95, v95, v2
	v_cndmask_b32_e64 v4, v3, 1.0, s[8:9]
	v_pk_add_f32 v[114:115], v[114:115], v[2:3] op_sel_hi:[1,0] neg_lo:[0,1] neg_hi:[0,1]
	v_pk_add_f32 v[98:99], v[98:99], v[2:3] op_sel_hi:[1,0] neg_lo:[0,1] neg_hi:[0,1]
	v_pk_add_f32 v[116:117], v[116:117], v[2:3] op_sel_hi:[1,0] neg_lo:[0,1] neg_hi:[0,1]
	v_pk_add_f32 v[100:101], v[100:101], v[2:3] op_sel_hi:[1,0] neg_lo:[0,1] neg_hi:[0,1]
	v_pk_add_f32 v[118:119], v[118:119], v[2:3] op_sel_hi:[1,0] neg_lo:[0,1] neg_hi:[0,1]
	v_pk_add_f32 v[102:103], v[102:103], v[2:3] op_sel_hi:[1,0] neg_lo:[0,1] neg_hi:[0,1]
	v_pk_add_f32 v[120:121], v[120:121], v[2:3] op_sel_hi:[1,0] neg_lo:[0,1] neg_hi:[0,1]
	v_pk_add_f32 v[104:105], v[104:105], v[2:3] op_sel_hi:[1,0] neg_lo:[0,1] neg_hi:[0,1]
	v_pk_add_f32 v[122:123], v[122:123], v[2:3] op_sel_hi:[1,0] neg_lo:[0,1] neg_hi:[0,1]
	v_pk_add_f32 v[106:107], v[106:107], v[2:3] op_sel_hi:[1,0] neg_lo:[0,1] neg_hi:[0,1]
	v_pk_add_f32 v[124:125], v[124:125], v[2:3] op_sel_hi:[1,0] neg_lo:[0,1] neg_hi:[0,1]
	v_pk_add_f32 v[108:109], v[108:109], v[2:3] op_sel_hi:[1,0] neg_lo:[0,1] neg_hi:[0,1]
	v_pk_add_f32 v[126:127], v[126:127], v[2:3] op_sel_hi:[1,0] neg_lo:[0,1] neg_hi:[0,1]
	v_pk_add_f32 v[110:111], v[110:111], v[2:3] op_sel_hi:[1,0] neg_lo:[0,1] neg_hi:[0,1]
	v_pk_add_f32 v[128:129], v[128:129], v[2:3] op_sel_hi:[1,0] neg_lo:[0,1] neg_hi:[0,1]
	v_pk_add_f32 v[112:113], v[112:113], v[2:3] op_sel_hi:[1,0] neg_lo:[0,1] neg_hi:[0,1]
	v_sub_f32_e32 v94, v94, v2
	v_sub_f32_e32 v93, v93, v2
	v_sub_f32_e32 v92, v92, v2
	v_sub_f32_e32 v91, v91, v2
	v_sub_f32_e32 v90, v90, v2
	v_sub_f32_e32 v89, v89, v2
	v_sub_f32_e32 v88, v88, v2
	v_sub_f32_e32 v87, v87, v2
	v_sub_f32_e32 v86, v86, v2
	v_sub_f32_e32 v85, v85, v2
	v_sub_f32_e32 v84, v84, v2
	v_sub_f32_e32 v83, v83, v2
	v_sub_f32_e32 v82, v82, v2
	s_cmp_eq_u64 s[8:9], exec
	s_cbranch_scc1 .Lattn_a1
	v_pk_mul_f32 v[80:81], v[80:81], v[4:5] op_sel_hi:[1,0]
	v_pk_mul_f32 v[78:79], v[78:79], v[4:5] op_sel_hi:[1,0]
	v_pk_mul_f32 v[76:77], v[76:77], v[4:5] op_sel_hi:[1,0]
	v_pk_mul_f32 v[74:75], v[74:75], v[4:5] op_sel_hi:[1,0]
	v_pk_mul_f32 v[72:73], v[72:73], v[4:5] op_sel_hi:[1,0]
	v_pk_mul_f32 v[70:71], v[70:71], v[4:5] op_sel_hi:[1,0]
	v_pk_mul_f32 v[68:69], v[68:69], v[4:5] op_sel_hi:[1,0]
	v_pk_mul_f32 v[66:67], v[66:67], v[4:5] op_sel_hi:[1,0]
	v_pk_mul_f32 v[64:65], v[64:65], v[4:5] op_sel_hi:[1,0]
	v_pk_mul_f32 v[62:63], v[62:63], v[4:5] op_sel_hi:[1,0]
	v_pk_mul_f32 v[60:61], v[60:61], v[4:5] op_sel_hi:[1,0]
	v_pk_mul_f32 v[58:59], v[58:59], v[4:5] op_sel_hi:[1,0]
	v_pk_mul_f32 v[56:57], v[56:57], v[4:5] op_sel_hi:[1,0]
	v_pk_mul_f32 v[54:55], v[54:55], v[4:5] op_sel_hi:[1,0]
	v_pk_mul_f32 v[52:53], v[52:53], v[4:5] op_sel_hi:[1,0]
	v_pk_mul_f32 v[50:51], v[50:51], v[4:5] op_sel_hi:[1,0]
	v_pk_mul_f32 v[48:49], v[48:49], v[4:5] op_sel_hi:[1,0]
	v_pk_mul_f32 v[46:47], v[46:47], v[4:5] op_sel_hi:[1,0]
	v_pk_mul_f32 v[44:45], v[44:45], v[4:5] op_sel_hi:[1,0]
	v_pk_mul_f32 v[42:43], v[42:43], v[4:5] op_sel_hi:[1,0]
	v_pk_mul_f32 v[40:41], v[40:41], v[4:5] op_sel_hi:[1,0]
	v_pk_mul_f32 v[38:39], v[38:39], v[4:5] op_sel_hi:[1,0]
	v_pk_mul_f32 v[36:37], v[36:37], v[4:5] op_sel_hi:[1,0]
	v_pk_mul_f32 v[34:35], v[34:35], v[4:5] op_sel_hi:[1,0]
	v_pk_mul_f32 v[32:33], v[32:33], v[4:5] op_sel_hi:[1,0]
	v_pk_mul_f32 v[30:31], v[30:31], v[4:5] op_sel_hi:[1,0]
	v_pk_mul_f32 v[28:29], v[28:29], v[4:5] op_sel_hi:[1,0]
	v_pk_mul_f32 v[26:27], v[26:27], v[4:5] op_sel_hi:[1,0]
	v_pk_mul_f32 v[24:25], v[24:25], v[4:5] op_sel_hi:[1,0]
	v_pk_mul_f32 v[22:23], v[22:23], v[4:5] op_sel_hi:[1,0]
	v_pk_mul_f32 v[20:21], v[20:21], v[4:5] op_sel_hi:[1,0]
	v_pk_mul_f32 v[18:19], v[18:19], v[4:5] op_sel_hi:[1,0]
	v_mul_f32_e32 v207, v207, v4
; __device__ __forceinline__ unsigned cvtpk(float lo, float hi) { f32x2 v = {lo, hi}; bf16x2_t b = __builtin_convertvector(v, bf16x2_t); return __builtin_bit_cast(unsigned, b); }
; __device__ __forceinline__ s16x4 vtr(LAS const unsigned char* p) { typedef short v4i16_t __attribute__((ext_vector_type(4))); return __builtin_bit_cast(s16x4, __builtin_amdgcn_ds_read_tr16_b64_v4i16((LAS v4i16_t*)p)); }
; __device__ __forceinline__ void attn_unit(const bf16* __restrict__ QB, const bf16* __restrict__ KB, const bf16* __restrict__ VB, bf16* __restrict__ YATT, ...
;     ...
;             float ps = 0.f;
; #pragma unroll
;             for (int r = 0; r < 16; ++r) { s0[r] = __builtin_amdgcn_exp2f(s0[r]); s1[r] = __builtin_amdgcn_exp2f(s1[r]); ps += s0[r] + s1[r]; }
;             lrun += ps;
;             bf16x8 pf[4];
; #pragma unroll
;             for (int s = 0; s < 4; ++s) {
;                 u32x4 w;
;                 if (s < 2) { const int o = 8 * s; w.x = cvtpk(s0[o], s0[o + 1]); w.y = cvtpk(s0[o + 2], s0[o + 3]); w.z = cvtpk(s0[o + 4], s0[o + 5]); w.w = cvtpk(s0[o + 6], s0[o + 7]); }
;                 else { const int o = 8 * (s - 2); w.x = cvtpk(s1[o], s1[o + 1]); w.y = cvtpk(s1[o + 2], s1[o + 3]); w.z = cvtpk(s1[o + 4], s1[o + 5]); w.w = cvtpk(s1[o + 6], s1[o + 7]); }
;                 pf[s] = __builtin_bit_cast(bf16x8, w);
;             }
; #pragma unroll
;             for (int s = 0; s < 4; ++s) {
; #pragma unroll
;                 for (int e = 0; e < 4; ++e) {
;                     const s16x4 lo = vtr(Vc + s * 4096 + e * 512), hv = vtr(Vc + s * 4096 + e * 512 + 2048);
;                     const bf16x8 vf = (bf16x8){lo[0], lo[1], lo[2], lo[3], hv[0], hv[1], hv[2], hv[3]};
;                     acc[e] = __builtin_amdgcn_mfma_f32_32x32x16_bf16(vf, pf[s], acc[e], 0, 0, 0);
;                 }
;             }
.Lattn_a1:
.LBB0_579:
	v_exp_f32_e32 v10, v114
	v_exp_f32_e32 v151, v98
	v_exp_f32_e32 v4, v115
	v_exp_f32_e32 v2, v99
	v_exp_f32_e32 v155, v100
	v_add_f32_e32 v209, v151, v10
	v_exp_f32_e32 v114, v101
	v_add_f32_e32 v210, v2, v4
	v_exp_f32_e32 v3, v116
	v_add_f32_e32 v209, v210, v209
	v_exp_f32_e32 v8, v117
	v_exp_f32_e32 v116, v103
	v_add_f32_e32 v210, v155, v3
	v_exp_f32_e32 v208, v106
	v_add_f32_e32 v209, v210, v209
	v_add_f32_e32 v210, v114, v8
	v_exp_f32_e32 v9, v118
	v_add_f32_e32 v209, v210, v209
	v_exp_f32_e32 v115, v102
	v_exp_f32_e32 v14, v119
	v_exp_f32_e32 v118, v105
	v_exp_f32_e32 v106, v107
	v_add_f32_e32 v210, v115, v9
	v_add_f32_e32 v209, v210, v209
	v_add_f32_e32 v210, v116, v14
	v_exp_f32_e32 v15, v120
	v_add_f32_e32 v209, v210, v209
	v_exp_f32_e32 v117, v104
	v_exp_f32_e32 v16, v121
	v_add_f32_e32 v210, v117, v15
	v_add_f32_e32 v209, v210, v209
	v_add_f32_e32 v210, v118, v16
	v_exp_f32_e32 v119, v122
	v_add_f32_e32 v209, v210, v209
	v_exp_f32_e32 v120, v123
	v_add_f32_e32 v210, v208, v119
	v_add_f32_e32 v209, v210, v209
	v_add_f32_e32 v210, v106, v120
	s_nop 0
	v_add_f32_e32 v209, v210, v209
	v_cvt_pk_bf16_f32 v7, v3, v8
	v_lshl_add_u32 v3, s86, 14, v201
	v_exp_f32_e32 v107, v124
	v_exp_f32_e32 v121, v108
	v_cvt_pk_bf16_f32 v6, v10, v4
	ds_read_b64_tr_b16 v[10:11], v3 offset:36864
	ds_read_b64_tr_b16 v[12:13], v3 offset:38912
	v_exp_f32_e32 v122, v125
	v_exp_f32_e32 v108, v109
	v_cvt_pk_bf16_f32 v8, v9, v14
	v_cvt_pk_bf16_f32 v9, v15, v16
	v_add_f32_e32 v210, v121, v107
	ds_read_b64_tr_b16 v[14:15], v3 offset:37376
	ds_read_b64_tr_b16 v[98:99], v3 offset:37888
	ds_read_b64_tr_b16 v[102:103], v3 offset:38400
	ds_read_b64_tr_b16 v[16:17], v3 offset:39424
	ds_read_b64_tr_b16 v[100:101], v3 offset:39936
	ds_read_b64_tr_b16 v[104:105], v3 offset:40448
	s_waitcnt lgkmcnt(6)
	v_mfma_f32_32x32x16_bf16 v[66:81], v[10:13], v[6:9], v[66:81]
	v_add_f32_e32 v209, v210, v209
	v_add_f32_e32 v210, v108, v122
	v_exp_f32_e32 v4, v126
	v_add_f32_e32 v209, v210, v209
	v_exp_f32_e32 v109, v110
	v_exp_f32_e32 v12, v127
	v_exp_f32_e32 v110, v111
	v_add_f32_e32 v210, v109, v4
	s_waitcnt lgkmcnt(2)
	v_mfma_f32_32x32x16_bf16 v[50:65], v[14:17], v[6:9], v[50:65]
	v_add_f32_e32 v209, v210, v209
	v_add_f32_e32 v210, v110, v12
	v_exp_f32_e32 v111, v128
	v_add_f32_e32 v209, v210, v209
	v_exp_f32_e32 v124, v129
	ds_read_b64_tr_b16 v[14:15], v3 offset:40960
	ds_read_b64_tr_b16 v[16:17], v3 offset:43008
	v_cvt_pk_bf16_f32 v10, v119, v120
	v_cvt_pk_bf16_f32 v11, v107, v122
	s_waitcnt lgkmcnt(3)
	v_mfma_f32_32x32x16_bf16 v[34:49], v[98:101], v[6:9], v[34:49]
	v_cvt_pk_bf16_f32 v12, v4, v12
	v_cvt_pk_bf16_f32 v13, v111, v124
	v_exp_f32_e32 v4, v112
	s_waitcnt lgkmcnt(2)
	v_mfma_f32_32x32x16_bf16 v[18:33], v[102:105], v[6:9], v[18:33]
	ds_read_b64_tr_b16 v[6:7], v3 offset:41472
	ds_read_b64_tr_b16 v[98:99], v3 offset:41984
	ds_read_b64_tr_b16 v[102:103], v3 offset:42496
	ds_read_b64_tr_b16 v[8:9], v3 offset:43520
	ds_read_b64_tr_b16 v[100:101], v3 offset:44032
	ds_read_b64_tr_b16 v[104:105], v3 offset:44544
	s_waitcnt lgkmcnt(6)
	v_mfma_f32_32x32x16_bf16 v[66:81], v[14:17], v[10:13], v[66:81]
	ds_read_b64_tr_b16 v[14:15], v3 offset:45056
	ds_read_b64_tr_b16 v[16:17], v3 offset:47104
	s_waitcnt lgkmcnt(4)
	v_mfma_f32_32x32x16_bf16 v[50:65], v[6:9], v[10:13], v[50:65]
	v_cvt_pk_bf16_f32 v6, v151, v2
	v_cvt_pk_bf16_f32 v7, v155, v114
	v_cvt_pk_bf16_f32 v8, v115, v116
	v_cvt_pk_bf16_f32 v9, v117, v118
	v_exp_f32_e32 v2, v113
	s_waitcnt lgkmcnt(3)
	v_mfma_f32_32x32x16_bf16 v[34:49], v[98:101], v[10:13], v[34:49]
	s_waitcnt lgkmcnt(2)
	v_mfma_f32_32x32x16_bf16 v[18:33], v[102:105], v[10:13], v[18:33]
	ds_read_b64_tr_b16 v[10:11], v3 offset:45568
	ds_read_b64_tr_b16 v[98:99], v3 offset:46080
	ds_read_b64_tr_b16 v[102:103], v3 offset:46592
	ds_read_b64_tr_b16 v[12:13], v3 offset:47616
	ds_read_b64_tr_b16 v[100:101], v3 offset:48128
	ds_read_b64_tr_b16 v[104:105], v3 offset:48640
	s_waitcnt lgkmcnt(6)
	v_mfma_f32_32x32x16_bf16 v[66:81], v[14:17], v[6:9], v[66:81]
	ds_read_b64_tr_b16 v[14:15], v3 offset:49152
	ds_read_b64_tr_b16 v[16:17], v3 offset:51200
	s_waitcnt lgkmcnt(4)
	v_mfma_f32_32x32x16_bf16 v[50:65], v[10:13], v[6:9], v[50:65]
	v_cvt_pk_bf16_f32 v10, v208, v106
	v_cvt_pk_bf16_f32 v11, v121, v108
	v_cvt_pk_bf16_f32 v12, v109, v110
	v_cvt_pk_bf16_f32 v13, v4, v2
	s_waitcnt lgkmcnt(3)
	v_mfma_f32_32x32x16_bf16 v[34:49], v[98:101], v[6:9], v[34:49]
	s_waitcnt lgkmcnt(2)
	v_mfma_f32_32x32x16_bf16 v[18:33], v[102:105], v[6:9], v[18:33]
	ds_read_b64_tr_b16 v[6:7], v3 offset:49664
	ds_read_b64_tr_b16 v[98:99], v3 offset:50176
	ds_read_b64_tr_b16 v[102:103], v3 offset:50688
	ds_read_b64_tr_b16 v[8:9], v3 offset:51712
	ds_read_b64_tr_b16 v[100:101], v3 offset:52224
	ds_read_b64_tr_b16 v[104:105], v3 offset:52736
	v_add_f32_e32 v210, v4, v111
	v_add_f32_e32 v209, v210, v209
	v_add_f32_e32 v210, v2, v124
	s_nop 0
	v_add_f32_e32 v209, v210, v209
	v_add_f32_e32 v207, v207, v209
	s_waitcnt lgkmcnt(6)
	v_mfma_f32_32x32x16_bf16 v[66:81], v[14:17], v[10:13], v[66:81]
	s_waitcnt lgkmcnt(2)
	v_mfma_f32_32x32x16_bf16 v[50:65], v[6:9], v[10:13], v[50:65]
	s_waitcnt lgkmcnt(1)
	v_mfma_f32_32x32x16_bf16 v[34:49], v[98:101], v[10:13], v[34:49]
	s_waitcnt lgkmcnt(0)
	v_mfma_f32_32x32x16_bf16 v[18:33], v[102:105], v[10:13], v[18:33]

; #define LAS __attribute__((address_space(3)))
; __device__ __forceinline__ unsigned cvtpk(float lo, float hi) { f32x2 v = {lo, hi}; bf16x2_t b = __builtin_convertvector(v, bf16x2_t); return __builtin_bit_cast(unsigned, b); }
; __device__ __forceinline__ void attn_unit(const bf16* __restrict__ QB, const bf16* __restrict__ KB, const bf16* __restrict__ VB, bf16* __restrict__ YATT, ...
;     ...
;     { auto rr = __builtin_amdgcn_permlane32_swap(__float_as_uint(lrun), __float_as_uint(lrun), false, false); lrun = __uint_as_float(rr[0]) + __uint_as_float(rr[1]); }
;     {
;         const float inv = 1.f / lrun;
;         LAS unsigned* stash = (LAS unsigned*)(lds + A_STASH) + w4 * 64 + lane;
;         if (jc == 0) {
; #pragma unroll
;             for (int e = 0; e < 4; ++e)
; #pragma unroll
;                 for (int i = 0; i < 8; ++i) stash[(e * 8 + i) * 256] = cvtpk(acc[e][2 * i] * inv, acc[e][2 * i + 1] * inv);
;         }
.LBB0_583:
	s_or_b64 exec, exec, s[92:93]
	v_readlane_b32 s98, v240, 3
	s_nop 3
	s_cmp_lg_u32 s98, 0
	s_cbranch_scc1 .Latk_b
	v_readlane_b32 s100, v240, 12
	v_readlane_b32 s101, v240, 13
	s_mov_b64 s[98:99], exec
	s_mov_b64 exec, 1
	v_mov_b32_e32 v244, 1
	v_mov_b32_e32 v245, 0
	s_nop 4
	global_atomic_add v244, v245, v244, s[100:101] sc0
	s_mov_b64 exec, s[98:99]
.Latk_b:
	v_mov_b32_e32 v2, v133
	s_nop 1
	v_permlane32_swap_b32_e32 v133, v2
	v_add_f32_e32 v2, v133, v2
	v_div_scale_f32 v3, s[4:5], v2, v2, 1.0
	v_rcp_f32_e32 v4, v3
	s_lshl_b32 s4, s75, 8
	s_add_i32 s4, s4, 0
	s_add_i32 s4, s4, 0x11000
	v_fma_f32 v6, -v3, v4, 1.0
	v_fmac_f32_e32 v4, v6, v4
	v_div_scale_f32 v6, vcc, 1.0, v2, 1.0
	v_mul_f32_e32 v7, v6, v4
	v_fma_f32 v8, -v3, v7, v6
	v_fmac_f32_e32 v7, v8, v4
	v_fma_f32 v3, -v3, v7, v6
	v_div_fmas_f32 v3, v3, v4, v7
	v_div_fixup_f32 v4, v3, v2, 1.0
	s_cmpk_gt_u32 s74, 0xff
	v_lshl_add_u32 v6, v195, 2, s4
	s_cbranch_scc1 .Lattn_sg
	v_pk_mul_f32 v[2:3], v[66:67], v[4:5] op_sel_hi:[1,0]
	s_nop 0
	v_cvt_pk_bf16_f32 v7, v2, v3
	v_pk_mul_f32 v[2:3], v[68:69], v[4:5] op_sel_hi:[1,0]
	s_nop 0
	v_cvt_pk_bf16_f32 v2, v2, v3
	ds_write2st64_b32 v6, v7, v2 offset1:4
	v_pk_mul_f32 v[2:3], v[70:71], v[4:5] op_sel_hi:[1,0]
	s_nop 0
	v_cvt_pk_bf16_f32 v7, v2, v3
	v_pk_mul_f32 v[2:3], v[72:73], v[4:5] op_sel_hi:[1,0]
	s_nop 0
	v_cvt_pk_bf16_f32 v2, v2, v3
	ds_write2st64_b32 v6, v7, v2 offset0:8 offset1:12
	v_pk_mul_f32 v[2:3], v[74:75], v[4:5] op_sel_hi:[1,0]
	s_nop 0
	v_cvt_pk_bf16_f32 v7, v2, v3
	v_pk_mul_f32 v[2:3], v[76:77], v[4:5] op_sel_hi:[1,0]
	s_nop 0
	v_cvt_pk_bf16_f32 v2, v2, v3
	ds_write2st64_b32 v6, v7, v2 offset0:16 offset1:20
	v_pk_mul_f32 v[2:3], v[78:79], v[4:5] op_sel_hi:[1,0]
	s_nop 0
	v_cvt_pk_bf16_f32 v7, v2, v3
	v_pk_mul_f32 v[2:3], v[80:81], v[4:5] op_sel_hi:[1,0]
	s_nop 0
	v_cvt_pk_bf16_f32 v2, v2, v3
	ds_write2st64_b32 v6, v7, v2 offset0:24 offset1:28
	v_pk_mul_f32 v[2:3], v[50:51], v[4:5] op_sel_hi:[1,0]
	s_nop 0
	v_cvt_pk_bf16_f32 v7, v2, v3
	v_pk_mul_f32 v[2:3], v[52:53], v[4:5] op_sel_hi:[1,0]
	s_nop 0
	v_cvt_pk_bf16_f32 v2, v2, v3
	ds_write2st64_b32 v6, v7, v2 offset0:32 offset1:36
	v_pk_mul_f32 v[2:3], v[54:55], v[4:5] op_sel_hi:[1,0]
	s_nop 0
	v_cvt_pk_bf16_f32 v7, v2, v3
	v_pk_mul_f32 v[2:3], v[56:57], v[4:5] op_sel_hi:[1,0]
	s_nop 0
	v_cvt_pk_bf16_f32 v2, v2, v3
	ds_write2st64_b32 v6, v7, v2 offset0:40 offset1:44
	v_pk_mul_f32 v[2:3], v[58:59], v[4:5] op_sel_hi:[1,0]
	s_nop 0
	v_cvt_pk_bf16_f32 v7, v2, v3
	v_pk_mul_f32 v[2:3], v[60:61], v[4:5] op_sel_hi:[1,0]
	s_nop 0
	v_cvt_pk_bf16_f32 v2, v2, v3
	ds_write2st64_b32 v6, v7, v2 offset0:48 offset1:52
	v_pk_mul_f32 v[2:3], v[62:63], v[4:5] op_sel_hi:[1,0]
	s_nop 0
	v_cvt_pk_bf16_f32 v7, v2, v3
	v_pk_mul_f32 v[2:3], v[64:65], v[4:5] op_sel_hi:[1,0]
	s_nop 0
	v_cvt_pk_bf16_f32 v2, v2, v3
	ds_write2st64_b32 v6, v7, v2 offset0:56 offset1:60
	v_pk_mul_f32 v[2:3], v[34:35], v[4:5] op_sel_hi:[1,0]
	s_nop 0
	v_cvt_pk_bf16_f32 v7, v2, v3
	v_pk_mul_f32 v[2:3], v[36:37], v[4:5] op_sel_hi:[1,0]
	s_nop 0
	v_cvt_pk_bf16_f32 v2, v2, v3
	ds_write2st64_b32 v6, v7, v2 offset0:64 offset1:68
	v_pk_mul_f32 v[2:3], v[38:39], v[4:5] op_sel_hi:[1,0]
	s_nop 0
	v_cvt_pk_bf16_f32 v7, v2, v3
	v_pk_mul_f32 v[2:3], v[40:41], v[4:5] op_sel_hi:[1,0]
	s_nop 0
	v_cvt_pk_bf16_f32 v2, v2, v3
	ds_write2st64_b32 v6, v7, v2 offset0:72 offset1:76
	v_pk_mul_f32 v[2:3], v[42:43], v[4:5] op_sel_hi:[1,0]
	s_nop 0
	v_cvt_pk_bf16_f32 v7, v2, v3
	v_pk_mul_f32 v[2:3], v[44:45], v[4:5] op_sel_hi:[1,0]
	s_nop 0
	v_cvt_pk_bf16_f32 v2, v2, v3
	ds_write2st64_b32 v6, v7, v2 offset0:80 offset1:84
	v_pk_mul_f32 v[2:3], v[46:47], v[4:5] op_sel_hi:[1,0]
	s_nop 0
	v_cvt_pk_bf16_f32 v7, v2, v3
	v_pk_mul_f32 v[2:3], v[48:49], v[4:5] op_sel_hi:[1,0]
	s_nop 0
	v_cvt_pk_bf16_f32 v2, v2, v3
	ds_write2st64_b32 v6, v7, v2 offset0:88 offset1:92
	v_pk_mul_f32 v[2:3], v[18:19], v[4:5] op_sel_hi:[1,0]
	s_nop 0
	v_cvt_pk_bf16_f32 v7, v2, v3
	v_pk_mul_f32 v[2:3], v[20:21], v[4:5] op_sel_hi:[1,0]
	s_nop 0
	v_cvt_pk_bf16_f32 v2, v2, v3
	ds_write2st64_b32 v6, v7, v2 offset0:96 offset1:100
	v_pk_mul_f32 v[2:3], v[22:23], v[4:5] op_sel_hi:[1,0]
	s_nop 0
	v_cvt_pk_bf16_f32 v7, v2, v3
	v_pk_mul_f32 v[2:3], v[24:25], v[4:5] op_sel_hi:[1,0]
	s_nop 0
	v_cvt_pk_bf16_f32 v2, v2, v3
	ds_write2st64_b32 v6, v7, v2 offset0:104 offset1:108
	v_pk_mul_f32 v[2:3], v[26:27], v[4:5] op_sel_hi:[1,0]
	s_nop 0
	v_cvt_pk_bf16_f32 v7, v2, v3
	v_pk_mul_f32 v[2:3], v[28:29], v[4:5] op_sel_hi:[1,0]
	s_nop 0
	v_cvt_pk_bf16_f32 v2, v2, v3
	ds_write2st64_b32 v6, v7, v2 offset0:112 offset1:116
	v_pk_mul_f32 v[2:3], v[30:31], v[4:5] op_sel_hi:[1,0]
	s_nop 0
	v_cvt_pk_bf16_f32 v7, v2, v3
	v_pk_mul_f32 v[2:3], v[32:33], v[4:5] op_sel_hi:[1,0]
	s_nop 0
	v_cvt_pk_bf16_f32 v2, v2, v3
	ds_write2st64_b32 v6, v7, v2 offset0:120 offset1:124
; __device__ __forceinline__ void attn_unit(const bf16* __restrict__ QB, const bf16* __restrict__ KB, const bf16* __restrict__ VB, bf16* __restrict__ YATT, ...
;     ...
;         __syncthreads();
;         if (jc == 1) {
;             float ss = 0.f;
; #pragma unroll
;             for (int e = 0; e < 4; ++e)
; #pragma unroll
;                 for (int i = 0; i < 8; ++i) { const unsigned w = stash[(e * 8 + i) * 256];
;                     const float o0 = bflo(w) - lam * (acc[e][2 * i] * inv), o1 = bfhi(w) - lam * (acc[e][2 * i + 1] * inv);
;                     acc[e][2 * i] = o0; acc[e][2 * i + 1] = o1; ss += o0 * o0 + o1 * o1; }
.LBB0_585:
	s_cmp_lg_u32 s38, 1
	s_waitcnt lgkmcnt(0)
	s_barrier
	s_cbranch_scc1 .LBB0_556
	ds_read2st64_b32 v[2:3], v6 offset1:4
	v_pk_mul_f32 v[8:9], v[66:67], v[4:5] op_sel_hi:[1,0]
	ds_read2st64_b32 v[14:15], v6 offset0:8 offset1:12
	v_pk_mul_f32 v[16:17], v[70:71], v[4:5] op_sel_hi:[1,0]
	ds_read2st64_b32 v[66:67], v6 offset0:16 offset1:20
	s_waitcnt lgkmcnt(2)
	v_lshlrev_b32_e32 v10, 16, v2
	v_and_b32_e32 v11, 0xffff0000, v2
	v_lshlrev_b32_e32 v12, 16, v3
	v_and_b32_e32 v13, 0xffff0000, v3
	v_pk_fma_f32 v[2:3], v[176:177], v[8:9], v[10:11] neg_lo:[1,0,0] neg_hi:[1,0,0]
	v_pk_mul_f32 v[10:11], v[68:69], v[4:5] op_sel_hi:[1,0]
	v_mul_f32_e32 v8, v3, v3
	v_pk_fma_f32 v[10:11], v[176:177], v[10:11], v[12:13] neg_lo:[1,0,0] neg_hi:[1,0,0]
	v_pk_fma_f32 v[8:9], v[2:3], v[2:3], v[8:9] op_sel_hi:[1,1,0]
	v_mul_f32_e32 v12, v11, v11
	v_pk_fma_f32 v[12:13], v[10:11], v[10:11], v[12:13] op_sel_hi:[1,1,0]
	v_pk_mul_f32 v[68:69], v[74:75], v[4:5] op_sel_hi:[1,0]
	v_pk_add_f32 v[8:9], v[8:9], v[12:13]
	s_waitcnt lgkmcnt(1)
	v_lshlrev_b32_e32 v12, 16, v14
	v_and_b32_e32 v13, 0xffff0000, v14
	v_pk_fma_f32 v[12:13], v[176:177], v[16:17], v[12:13] neg_lo:[1,0,0] neg_hi:[1,0,0]
	ds_read2st64_b32 v[70:71], v6 offset0:24 offset1:28
	v_mul_f32_e32 v14, v13, v13
	v_pk_fma_f32 v[16:17], v[12:13], v[12:13], v[14:15] op_sel_hi:[1,1,0]
	v_lshlrev_b32_e32 v14, 16, v15
	v_pk_add_f32 v[8:9], v[8:9], v[16:17]
	v_and_b32_e32 v15, 0xffff0000, v15
	v_pk_mul_f32 v[16:17], v[72:73], v[4:5] op_sel_hi:[1,0]
	v_pk_mul_f32 v[72:73], v[78:79], v[4:5] op_sel_hi:[1,0]
	v_pk_fma_f32 v[14:15], v[176:177], v[16:17], v[14:15] neg_lo:[1,0,0] neg_hi:[1,0,0]
	ds_read2st64_b32 v[74:75], v6 offset0:32 offset1:36
	v_mul_f32_e32 v16, v15, v15
	v_pk_fma_f32 v[16:17], v[14:15], v[14:15], v[16:17] op_sel_hi:[1,1,0]
	v_pk_mul_f32 v[50:51], v[50:51], v[4:5] op_sel_hi:[1,0]
	v_pk_add_f32 v[8:9], v[8:9], v[16:17]
	s_waitcnt lgkmcnt(2)
	v_lshlrev_b32_e32 v16, 16, v66
	v_and_b32_e32 v17, 0xffff0000, v66
	v_pk_fma_f32 v[16:17], v[176:177], v[68:69], v[16:17] neg_lo:[1,0,0] neg_hi:[1,0,0]
	v_pk_mul_f32 v[52:53], v[52:53], v[4:5] op_sel_hi:[1,0]
	v_mul_f32_e32 v66, v17, v17
	v_pk_fma_f32 v[68:69], v[16:17], v[16:17], v[66:67] op_sel_hi:[1,1,0]
	v_lshlrev_b32_e32 v66, 16, v67
	v_pk_add_f32 v[8:9], v[8:9], v[68:69]
	v_and_b32_e32 v67, 0xffff0000, v67
	v_pk_mul_f32 v[68:69], v[76:77], v[4:5] op_sel_hi:[1,0]
	v_pk_mul_f32 v[54:55], v[54:55], v[4:5] op_sel_hi:[1,0]
	v_pk_fma_f32 v[66:67], v[176:177], v[68:69], v[66:67] neg_lo:[1,0,0] neg_hi:[1,0,0]
	v_pk_mul_f32 v[56:57], v[56:57], v[4:5] op_sel_hi:[1,0]
	v_mul_f32_e32 v68, v67, v67
	v_pk_fma_f32 v[68:69], v[66:67], v[66:67], v[68:69] op_sel_hi:[1,1,0]
	v_pk_mul_f32 v[58:59], v[58:59], v[4:5] op_sel_hi:[1,0]
	v_pk_add_f32 v[8:9], v[8:9], v[68:69]
	s_waitcnt lgkmcnt(1)
	v_lshlrev_b32_e32 v68, 16, v70
	v_and_b32_e32 v69, 0xffff0000, v70
	v_pk_fma_f32 v[68:69], v[176:177], v[72:73], v[68:69] neg_lo:[1,0,0] neg_hi:[1,0,0]
	ds_read2st64_b32 v[76:77], v6 offset0:56 offset1:60
	v_mul_f32_e32 v70, v69, v69
	v_pk_fma_f32 v[72:73], v[68:69], v[68:69], v[70:71] op_sel_hi:[1,1,0]
	v_lshlrev_b32_e32 v70, 16, v71
	v_pk_add_f32 v[8:9], v[8:9], v[72:73]
	v_and_b32_e32 v71, 0xffff0000, v71
	v_pk_mul_f32 v[72:73], v[80:81], v[4:5] op_sel_hi:[1,0]
	v_pk_mul_f32 v[60:61], v[60:61], v[4:5] op_sel_hi:[1,0]
	v_pk_fma_f32 v[70:71], v[176:177], v[72:73], v[70:71] neg_lo:[1,0,0] neg_hi:[1,0,0]
	v_pk_mul_f32 v[34:35], v[34:35], v[4:5] op_sel_hi:[1,0]
	v_mul_f32_e32 v72, v71, v71
	v_pk_fma_f32 v[72:73], v[70:71], v[70:71], v[72:73] op_sel_hi:[1,1,0]
	v_pk_mul_f32 v[36:37], v[36:37], v[4:5] op_sel_hi:[1,0]
	v_pk_add_f32 v[8:9], v[8:9], v[72:73]
	s_waitcnt lgkmcnt(1)
	v_lshlrev_b32_e32 v72, 16, v74
	v_and_b32_e32 v73, 0xffff0000, v74
	v_pk_fma_f32 v[50:51], v[176:177], v[50:51], v[72:73] neg_lo:[1,0,0] neg_hi:[1,0,0]
	v_pk_mul_f32 v[38:39], v[38:39], v[4:5] op_sel_hi:[1,0]
	v_mul_f32_e32 v72, v51, v51
	v_pk_fma_f32 v[72:73], v[50:51], v[50:51], v[72:73] op_sel_hi:[1,1,0]
	v_pk_mul_f32 v[40:41], v[40:41], v[4:5] op_sel_hi:[1,0]
	v_pk_add_f32 v[8:9], v[8:9], v[72:73]
	v_lshlrev_b32_e32 v72, 16, v75
	v_and_b32_e32 v73, 0xffff0000, v75
	ds_read2st64_b32 v[74:75], v6 offset0:40 offset1:44
	v_pk_fma_f32 v[52:53], v[176:177], v[52:53], v[72:73] neg_lo:[1,0,0] neg_hi:[1,0,0]
	v_pk_mul_f32 v[42:43], v[42:43], v[4:5] op_sel_hi:[1,0]
	v_mul_f32_e32 v72, v53, v53
	v_pk_fma_f32 v[72:73], v[52:53], v[52:53], v[72:73] op_sel_hi:[1,1,0]
	v_pk_mul_f32 v[44:45], v[44:45], v[4:5] op_sel_hi:[1,0]
	v_pk_add_f32 v[8:9], v[8:9], v[72:73]
	s_waitcnt lgkmcnt(0)
	v_lshlrev_b32_e32 v72, 16, v74
	v_and_b32_e32 v73, 0xffff0000, v74
	v_pk_fma_f32 v[54:55], v[176:177], v[54:55], v[72:73] neg_lo:[1,0,0] neg_hi:[1,0,0]
	v_pk_mul_f32 v[46:47], v[46:47], v[4:5] op_sel_hi:[1,0]
	v_mul_f32_e32 v72, v55, v55
	v_pk_fma_f32 v[72:73], v[54:55], v[54:55], v[72:73] op_sel_hi:[1,1,0]
	v_pk_mul_f32 v[48:49], v[48:49], v[4:5] op_sel_hi:[1,0]
	v_pk_add_f32 v[8:9], v[8:9], v[72:73]
	v_lshlrev_b32_e32 v72, 16, v75
	v_and_b32_e32 v73, 0xffff0000, v75
	ds_read2st64_b32 v[74:75], v6 offset0:48 offset1:52
	v_pk_fma_f32 v[72:73], v[176:177], v[56:57], v[72:73] neg_lo:[1,0,0] neg_hi:[1,0,0]
	v_pk_mul_f32 v[18:19], v[18:19], v[4:5] op_sel_hi:[1,0]
	v_mul_f32_e32 v56, v73, v73
	v_pk_fma_f32 v[56:57], v[72:73], v[72:73], v[56:57] op_sel_hi:[1,1,0]
	v_pk_mul_f32 v[20:21], v[20:21], v[4:5] op_sel_hi:[1,0]
	v_pk_add_f32 v[8:9], v[8:9], v[56:57]
	s_waitcnt lgkmcnt(0)
; __device__ __forceinline__ void attn_unit(const bf16* __restrict__ QB, const bf16* __restrict__ KB, const bf16* __restrict__ VB, bf16* __restrict__ YATT, ...
;     ...
;         __syncthreads();
;         if (jc == 1) {
;             float ss = 0.f;
; #pragma unroll
;             for (int e = 0; e < 4; ++e)
; #pragma unroll
;                 for (int i = 0; i < 8; ++i) { const unsigned w = stash[(e * 8 + i) * 256];
;                     const float o0 = bflo(w) - lam * (acc[e][2 * i] * inv), o1 = bfhi(w) - lam * (acc[e][2 * i + 1] * inv);
;                     acc[e][2 * i] = o0; acc[e][2 * i + 1] = o1; ss += o0 * o0 + o1 * o1; }
	v_lshlrev_b32_e32 v56, 16, v74
	v_and_b32_e32 v57, 0xffff0000, v74
	v_pk_fma_f32 v[58:59], v[176:177], v[58:59], v[56:57] neg_lo:[1,0,0] neg_hi:[1,0,0]
	v_pk_mul_f32 v[22:23], v[22:23], v[4:5] op_sel_hi:[1,0]
	v_mul_f32_e32 v56, v59, v59
	v_pk_fma_f32 v[56:57], v[58:59], v[58:59], v[56:57] op_sel_hi:[1,1,0]
	v_pk_mul_f32 v[24:25], v[24:25], v[4:5] op_sel_hi:[1,0]
	v_pk_add_f32 v[8:9], v[8:9], v[56:57]
	v_lshlrev_b32_e32 v56, 16, v75
	v_and_b32_e32 v57, 0xffff0000, v75
	v_pk_fma_f32 v[74:75], v[176:177], v[60:61], v[56:57] neg_lo:[1,0,0] neg_hi:[1,0,0]
	v_pk_mul_f32 v[60:61], v[62:63], v[4:5] op_sel_hi:[1,0]
	v_mul_f32_e32 v56, v75, v75
	v_pk_fma_f32 v[56:57], v[74:75], v[74:75], v[56:57] op_sel_hi:[1,1,0]
	v_pk_mul_f32 v[62:63], v[64:65], v[4:5] op_sel_hi:[1,0]
	v_pk_add_f32 v[8:9], v[8:9], v[56:57]
	v_lshlrev_b32_e32 v56, 16, v76
	v_and_b32_e32 v57, 0xffff0000, v76
	v_pk_fma_f32 v[56:57], v[176:177], v[60:61], v[56:57] neg_lo:[1,0,0] neg_hi:[1,0,0]
	ds_read2st64_b32 v[64:65], v6 offset0:64 offset1:68
	v_mul_f32_e32 v60, v57, v57
	v_pk_fma_f32 v[60:61], v[56:57], v[56:57], v[60:61] op_sel_hi:[1,1,0]
	v_pk_mul_f32 v[26:27], v[26:27], v[4:5] op_sel_hi:[1,0]
	v_pk_add_f32 v[8:9], v[8:9], v[60:61]
	v_lshlrev_b32_e32 v60, 16, v77
	v_and_b32_e32 v61, 0xffff0000, v77
	v_pk_fma_f32 v[60:61], v[176:177], v[62:63], v[60:61] neg_lo:[1,0,0] neg_hi:[1,0,0]
	v_pk_mul_f32 v[28:29], v[28:29], v[4:5] op_sel_hi:[1,0]
	v_mul_f32_e32 v62, v61, v61
	v_pk_fma_f32 v[62:63], v[60:61], v[60:61], v[62:63] op_sel_hi:[1,1,0]
	v_pk_mul_f32 v[30:31], v[30:31], v[4:5] op_sel_hi:[1,0]
	v_pk_add_f32 v[8:9], v[8:9], v[62:63]
	s_waitcnt lgkmcnt(0)
	v_lshlrev_b32_e32 v62, 16, v64
	v_and_b32_e32 v63, 0xffff0000, v64
	v_pk_fma_f32 v[34:35], v[176:177], v[34:35], v[62:63] neg_lo:[1,0,0] neg_hi:[1,0,0]
	v_pk_mul_f32 v[32:33], v[32:33], v[4:5] op_sel_hi:[1,0]
	v_mul_f32_e32 v62, v35, v35
	v_pk_fma_f32 v[62:63], v[34:35], v[34:35], v[62:63] op_sel_hi:[1,1,0]
	s_nop 0
	v_pk_add_f32 v[8:9], v[8:9], v[62:63]
	v_lshlrev_b32_e32 v62, 16, v65
	v_and_b32_e32 v63, 0xffff0000, v65
	ds_read2st64_b32 v[64:65], v6 offset0:72 offset1:76
	v_pk_fma_f32 v[36:37], v[176:177], v[36:37], v[62:63] neg_lo:[1,0,0] neg_hi:[1,0,0]
	s_nop 0
	v_mul_f32_e32 v62, v37, v37
	v_pk_fma_f32 v[62:63], v[36:37], v[36:37], v[62:63] op_sel_hi:[1,1,0]
	s_nop 0
	v_pk_add_f32 v[8:9], v[8:9], v[62:63]
	s_waitcnt lgkmcnt(0)
	v_lshlrev_b32_e32 v62, 16, v64
	v_and_b32_e32 v63, 0xffff0000, v64
	v_pk_fma_f32 v[38:39], v[176:177], v[38:39], v[62:63] neg_lo:[1,0,0] neg_hi:[1,0,0]
	s_nop 0
	v_mul_f32_e32 v62, v39, v39
	v_pk_fma_f32 v[62:63], v[38:39], v[38:39], v[62:63] op_sel_hi:[1,1,0]
	s_nop 0
	v_pk_add_f32 v[8:9], v[8:9], v[62:63]
	v_lshlrev_b32_e32 v62, 16, v65
	v_and_b32_e32 v63, 0xffff0000, v65
	ds_read2st64_b32 v[64:65], v6 offset0:80 offset1:84
	v_pk_fma_f32 v[40:41], v[176:177], v[40:41], v[62:63] neg_lo:[1,0,0] neg_hi:[1,0,0]
	s_nop 0
	v_mul_f32_e32 v62, v41, v41
	v_pk_fma_f32 v[62:63], v[40:41], v[40:41], v[62:63] op_sel_hi:[1,1,0]
	s_nop 0
	v_pk_add_f32 v[8:9], v[8:9], v[62:63]
	s_waitcnt lgkmcnt(0)
	v_lshlrev_b32_e32 v62, 16, v64
	v_and_b32_e32 v63, 0xffff0000, v64
	v_pk_fma_f32 v[42:43], v[176:177], v[42:43], v[62:63] neg_lo:[1,0,0] neg_hi:[1,0,0]
	s_nop 0
	v_mul_f32_e32 v62, v43, v43
	v_pk_fma_f32 v[62:63], v[42:43], v[42:43], v[62:63] op_sel_hi:[1,1,0]
	s_nop 0
	v_pk_add_f32 v[8:9], v[8:9], v[62:63]
	v_lshlrev_b32_e32 v62, 16, v65
	v_and_b32_e32 v63, 0xffff0000, v65
	ds_read2st64_b32 v[64:65], v6 offset0:88 offset1:92
	v_pk_fma_f32 v[44:45], v[176:177], v[44:45], v[62:63] neg_lo:[1,0,0] neg_hi:[1,0,0]
	s_nop 0
	v_mul_f32_e32 v62, v45, v45
	v_pk_fma_f32 v[62:63], v[44:45], v[44:45], v[62:63] op_sel_hi:[1,1,0]
	s_nop 0
	v_pk_add_f32 v[8:9], v[8:9], v[62:63]
	s_waitcnt lgkmcnt(0)
	v_lshlrev_b32_e32 v62, 16, v64
	v_and_b32_e32 v63, 0xffff0000, v64
	v_pk_fma_f32 v[46:47], v[176:177], v[46:47], v[62:63] neg_lo:[1,0,0] neg_hi:[1,0,0]
	s_nop 0
	v_mul_f32_e32 v62, v47, v47
	v_pk_fma_f32 v[62:63], v[46:47], v[46:47], v[62:63] op_sel_hi:[1,1,0]
	s_nop 0
	v_pk_add_f32 v[8:9], v[8:9], v[62:63]
	v_lshlrev_b32_e32 v62, 16, v65
	v_and_b32_e32 v63, 0xffff0000, v65
	ds_read2st64_b32 v[64:65], v6 offset0:96 offset1:100
	v_pk_fma_f32 v[48:49], v[176:177], v[48:49], v[62:63] neg_lo:[1,0,0] neg_hi:[1,0,0]
	s_nop 0
	v_mul_f32_e32 v62, v49, v49
	v_pk_fma_f32 v[62:63], v[48:49], v[48:49], v[62:63] op_sel_hi:[1,1,0]
	s_nop 0
	v_pk_add_f32 v[8:9], v[8:9], v[62:63]
	s_waitcnt lgkmcnt(0)
	v_lshlrev_b32_e32 v62, 16, v64
	v_and_b32_e32 v63, 0xffff0000, v64
	v_pk_fma_f32 v[18:19], v[176:177], v[18:19], v[62:63] neg_lo:[1,0,0] neg_hi:[1,0,0]
	s_nop 0
	v_mul_f32_e32 v62, v19, v19
	v_pk_fma_f32 v[62:63], v[18:19], v[18:19], v[62:63] op_sel_hi:[1,1,0]
	s_nop 0
	v_pk_add_f32 v[8:9], v[8:9], v[62:63]
	v_lshlrev_b32_e32 v62, 16, v65
	v_and_b32_e32 v63, 0xffff0000, v65
	ds_read2st64_b32 v[64:65], v6 offset0:104 offset1:108
	v_pk_fma_f32 v[20:21], v[176:177], v[20:21], v[62:63] neg_lo:[1,0,0] neg_hi:[1,0,0]
	s_nop 0
	v_mul_f32_e32 v62, v21, v21
	v_pk_fma_f32 v[62:63], v[20:21], v[20:21], v[62:63] op_sel_hi:[1,1,0]
	s_nop 0
	v_pk_add_f32 v[8:9], v[8:9], v[62:63]
	s_waitcnt lgkmcnt(0)
	v_lshlrev_b32_e32 v62, 16, v64
	v_and_b32_e32 v63, 0xffff0000, v64
	v_pk_fma_f32 v[22:23], v[176:177], v[22:23], v[62:63] neg_lo:[1,0,0] neg_hi:[1,0,0]
	s_nop 0
	v_mul_f32_e32 v62, v23, v23
	v_pk_fma_f32 v[62:63], v[22:23], v[22:23], v[62:63] op_sel_hi:[1,1,0]
	s_nop 0
	v_pk_add_f32 v[8:9], v[8:9], v[62:63]
	v_lshlrev_b32_e32 v62, 16, v65
	v_and_b32_e32 v63, 0xffff0000, v65
	ds_read2st64_b32 v[64:65], v6 offset0:112 offset1:116
	v_pk_fma_f32 v[24:25], v[176:177], v[24:25], v[62:63] neg_lo:[1,0,0] neg_hi:[1,0,0]
	ds_read2st64_b32 v[6:7], v6 offset0:120 offset1:124
	v_mul_f32_e32 v62, v25, v25
	v_pk_fma_f32 v[62:63], v[24:25], v[24:25], v[62:63] op_sel_hi:[1,1,0]
	s_nop 0
	v_pk_add_f32 v[8:9], v[8:9], v[62:63]
	s_waitcnt lgkmcnt(1)
; __device__ __forceinline__ void attn_unit(const bf16* __restrict__ QB, const bf16* __restrict__ KB, const bf16* __restrict__ VB, bf16* __restrict__ YATT, ...
;     ...
;                 for (int i = 0; i < 8; ++i) { const unsigned w = stash[(e * 8 + i) * 256];
;                     const float o0 = bflo(w) - lam * (acc[e][2 * i] * inv), o1 = bfhi(w) - lam * (acc[e][2 * i + 1] * inv);
;                     acc[e][2 * i] = o0; acc[e][2 * i + 1] = o1; ss += o0 * o0 + o1 * o1; }
;             { auto rr = __builtin_amdgcn_permlane32_swap(__float_as_uint(ss), __float_as_uint(ss), false, false); ss = __uint_as_float(rr[0]) + __uint_as_float(rr[1]); }
;             const float rn = __builtin_amdgcn_rsqf(ss * (1.f / 128.f) + EPS) * 0.8f;
;             if (tq >= 0 && jmax >= 0) {
	v_lshlrev_b32_e32 v62, 16, v64
	v_and_b32_e32 v63, 0xffff0000, v64
	v_pk_fma_f32 v[26:27], v[176:177], v[26:27], v[62:63] neg_lo:[1,0,0] neg_hi:[1,0,0]
	s_nop 0
	v_mul_f32_e32 v62, v27, v27
	v_pk_fma_f32 v[62:63], v[26:27], v[26:27], v[62:63] op_sel_hi:[1,1,0]
	s_nop 0
	v_pk_add_f32 v[8:9], v[8:9], v[62:63]
	v_lshlrev_b32_e32 v62, 16, v65
	v_and_b32_e32 v63, 0xffff0000, v65
	v_pk_fma_f32 v[28:29], v[176:177], v[28:29], v[62:63] neg_lo:[1,0,0] neg_hi:[1,0,0]
	s_nop 0
	v_mul_f32_e32 v62, v29, v29
	v_pk_fma_f32 v[62:63], v[28:29], v[28:29], v[62:63] op_sel_hi:[1,1,0]
	s_nop 0
	v_pk_add_f32 v[8:9], v[8:9], v[62:63]
	s_waitcnt lgkmcnt(0)
	v_lshlrev_b32_e32 v62, 16, v6
	v_and_b32_e32 v63, 0xffff0000, v6
	v_pk_fma_f32 v[30:31], v[176:177], v[30:31], v[62:63] neg_lo:[1,0,0] neg_hi:[1,0,0]
	s_nop 0
	v_mul_f32_e32 v6, v31, v31
	v_pk_fma_f32 v[62:63], v[30:31], v[30:31], v[6:7] op_sel_hi:[1,1,0]
	v_lshlrev_b32_e32 v6, 16, v7
	v_and_b32_e32 v7, 0xffff0000, v7
	v_pk_fma_f32 v[32:33], v[176:177], v[32:33], v[6:7] neg_lo:[1,0,0] neg_hi:[1,0,0]
	v_pk_add_f32 v[8:9], v[8:9], v[62:63]
	v_mul_f32_e32 v4, v33, v33
	v_pk_fma_f32 v[6:7], v[32:33], v[32:33], v[4:5] op_sel_hi:[1,1,0]
	s_nop 0
	v_pk_add_f32 v[62:63], v[8:9], v[6:7]
	v_or_b32_e32 v6, s73, v194
	v_mov_b32_e32 v4, v62
	s_nop 1
	v_permlane32_swap_b32_e32 v62, v4
	v_cmp_lt_i32_e32 vcc, -1, v6
	s_waitcnt vmcnt(0)
	s_and_saveexec_b64 s[4:5], vcc
	s_cbranch_execz .LBB0_555
; __device__ __forceinline__ unsigned cvtpk(float lo, float hi) { f32x2 v = {lo, hi}; bf16x2_t b = __builtin_convertvector(v, bf16x2_t); return __builtin_bit_cast(unsigned, b); }
; __device__ __forceinline__ void attn_unit(const bf16* __restrict__ QB, const bf16* __restrict__ KB, const bf16* __restrict__ VB, bf16* __restrict__ YATT, ...
;     ...
;             if (tq >= 0 && jmax >= 0) {
;                 const int orow = tq < NMETA ? MAINR + tq : b * SEQ + tq - NMETA;
;                 bf16* op = YATT + (size_t)orow * 512 + h * 128 + 4 * hi;
; #pragma unroll
;                 for (int e = 0; e < 4; ++e)
; #pragma unroll
;                     for (int i = 0; i < 4; ++i) { const f32x4 g = *(const f32x4*)(sg + 32 * e + 8 * i + 4 * hi);
;                         u32x2 w; w.x = cvtpk(acc[e][4 * i] * rn * g[0], acc[e][4 * i + 1] * rn * g[1]); w.y = cvtpk(acc[e][4 * i + 2] * rn * g[2], acc[e][4 * i + 3] * rn * g[3]); *(u32x2*)(op + 32 * e + 8 * i) = w; }
;             }
	v_add_f32_e32 v4, v62, v4
	s_lshl_b32 s8, s72, 12
	v_fmamk_f32 v4, v4, 0x3c000000, v1
	s_add_i32 s8, s8, -16
	v_rsq_f32_e32 v134, v4
	v_mov_b32_e32 v4, s8
	v_cmp_lt_u32_e32 vcc, 15, v194
	s_mov_b64 s[6:7], 0x1af00000
	v_mul_f32_e32 v134, 0x3f4ccccd, v134
	v_cndmask_b32_e32 v4, v193, v4, vcc
	v_add_u32_e32 v4, v4, v194
	v_lshlrev_b64 v[132:133], 10, v[4:5]
	v_lshl_add_u64 v[132:133], s[88:89], 0, v[132:133]
	v_lshlrev_b32_e32 v4, 1, v179
	v_lshl_add_u64 v[132:133], v[132:133], 0, s[82:83]
	s_mov_b32 s9, 0x1af00000
	v_pk_mul_f32 v[2:3], v[2:3], v[134:135] op_sel_hi:[1,0]
	v_pk_mul_f32 v[10:11], v[10:11], v[134:135] op_sel_hi:[1,0]
	v_pk_mul_f32 v[12:13], v[12:13], v[134:135] op_sel_hi:[1,0]
	v_pk_mul_f32 v[14:15], v[14:15], v[134:135] op_sel_hi:[1,0]
	v_lshl_add_u64 v[132:133], v[132:133], 0, v[4:5]
	v_pk_mul_f32 v[16:17], v[16:17], v[134:135] op_sel_hi:[1,0]
	v_pk_mul_f32 v[66:67], v[66:67], v[134:135] op_sel_hi:[1,0]
	v_pk_mul_f32 v[68:69], v[68:69], v[134:135] op_sel_hi:[1,0]
	v_pk_mul_f32 v[70:71], v[70:71], v[134:135] op_sel_hi:[1,0]
	v_pk_mul_f32 v[50:51], v[50:51], v[134:135] op_sel_hi:[1,0]
	v_pk_mul_f32 v[52:53], v[52:53], v[134:135] op_sel_hi:[1,0]
	v_pk_mul_f32 v[54:55], v[54:55], v[134:135] op_sel_hi:[1,0]
	v_pk_mul_f32 v[72:73], v[72:73], v[134:135] op_sel_hi:[1,0]
	v_lshl_add_u64 v[136:137], v[132:133], 0, s[6:7]
	v_add_co_u32_e32 v132, vcc, s9, v132
	v_pk_mul_f32 v[58:59], v[58:59], v[134:135] op_sel_hi:[1,0]
	s_nop 0
	v_addc_co_u32_e32 v133, vcc, 0, v133, vcc
	v_pk_mul_f32 v[74:75], v[74:75], v[134:135] op_sel_hi:[1,0]
	v_pk_mul_f32 v[2:3], v[2:3], v[140:141]
	v_pk_mul_f32 v[6:7], v[10:11], v[142:143]
	v_pk_mul_f32 v[8:9], v[12:13], v[144:145]
	v_pk_mul_f32 v[10:11], v[14:15], v[146:147]
	v_pk_mul_f32 v[12:13], v[16:17], v[160:161]
	v_pk_mul_f32 v[14:15], v[66:67], v[162:163]
	v_pk_mul_f32 v[16:17], v[68:69], v[84:85]
	v_pk_mul_f32 v[66:67], v[70:71], v[86:87]
	v_pk_mul_f32 v[50:51], v[50:51], v[88:89]
	v_pk_mul_f32 v[52:53], v[52:53], v[90:91]
	v_pk_mul_f32 v[54:55], v[54:55], v[92:93]
	v_pk_mul_f32 v[68:69], v[72:73], v[94:95]
	v_cvt_pk_bf16_f32 v2, v2, v3
	v_cvt_pk_bf16_f32 v3, v6, v7
	v_cvt_pk_bf16_f32 v6, v8, v9
	v_cvt_pk_bf16_f32 v7, v10, v11
	v_cvt_pk_bf16_f32 v8, v12, v13
	v_cvt_pk_bf16_f32 v9, v14, v15
	v_cvt_pk_bf16_f32 v10, v16, v17
	v_cvt_pk_bf16_f32 v11, v66, v67
	v_cvt_pk_bf16_f32 v12, v50, v51
	v_cvt_pk_bf16_f32 v13, v52, v53
	v_cvt_pk_bf16_f32 v14, v54, v55
	v_cvt_pk_bf16_f32 v15, v68, v69
	global_store_dwordx2 v[132:133], v[2:3], off
	global_store_dwordx2 v[136:137], v[6:7], off offset:16
	global_store_dwordx2 v[136:137], v[8:9], off offset:32
	global_store_dwordx2 v[136:137], v[10:11], off offset:48
	global_store_dwordx2 v[136:137], v[12:13], off offset:64
	global_store_dwordx2 v[136:137], v[14:15], off offset:80
	v_pk_mul_f32 v[2:3], v[56:57], v[134:135] op_sel_hi:[1,0]
	v_pk_mul_f32 v[6:7], v[60:61], v[134:135] op_sel_hi:[1,0]
	v_pk_mul_f32 v[2:3], v[2:3], v[164:165]
	v_pk_mul_f32 v[6:7], v[6:7], v[166:167]
	v_cvt_pk_bf16_f32 v2, v2, v3
	v_cvt_pk_bf16_f32 v3, v6, v7
	global_store_dwordx2 v[136:137], v[2:3], off offset:112
	v_pk_mul_f32 v[2:3], v[34:35], v[134:135] op_sel_hi:[1,0]
	v_pk_mul_f32 v[6:7], v[36:37], v[134:135] op_sel_hi:[1,0]
	v_pk_mul_f32 v[2:3], v[2:3], v[100:101]
	v_pk_mul_f32 v[6:7], v[6:7], v[102:103]
	v_cvt_pk_bf16_f32 v2, v2, v3
	v_cvt_pk_bf16_f32 v3, v6, v7
	global_store_dwordx2 v[136:137], v[2:3], off offset:128
	v_pk_mul_f32 v[2:3], v[38:39], v[134:135] op_sel_hi:[1,0]
	v_pk_mul_f32 v[6:7], v[40:41], v[134:135] op_sel_hi:[1,0]
	v_pk_mul_f32 v[2:3], v[2:3], v[104:105]
	v_pk_mul_f32 v[6:7], v[6:7], v[106:107]
	v_cvt_pk_bf16_f32 v2, v2, v3
	v_cvt_pk_bf16_f32 v3, v6, v7
	global_store_dwordx2 v[136:137], v[2:3], off offset:144
	v_pk_mul_f32 v[2:3], v[42:43], v[134:135] op_sel_hi:[1,0]
	v_pk_mul_f32 v[6:7], v[44:45], v[134:135] op_sel_hi:[1,0]
	v_pk_mul_f32 v[2:3], v[2:3], v[108:109]
	v_pk_mul_f32 v[6:7], v[6:7], v[110:111]
	v_cvt_pk_bf16_f32 v2, v2, v3
	v_cvt_pk_bf16_f32 v3, v6, v7
	global_store_dwordx2 v[136:137], v[2:3], off offset:160
	v_pk_mul_f32 v[2:3], v[46:47], v[134:135] op_sel_hi:[1,0]
	v_pk_mul_f32 v[6:7], v[48:49], v[134:135] op_sel_hi:[1,0]
	v_pk_mul_f32 v[2:3], v[2:3], v[112:113]
	v_pk_mul_f32 v[6:7], v[6:7], v[114:115]
	v_cvt_pk_bf16_f32 v2, v2, v3
	v_cvt_pk_bf16_f32 v3, v6, v7
	global_store_dwordx2 v[136:137], v[2:3], off offset:176
	v_pk_mul_f32 v[2:3], v[18:19], v[134:135] op_sel_hi:[1,0]
	v_pk_mul_f32 v[6:7], v[20:21], v[134:135] op_sel_hi:[1,0]
	v_pk_mul_f32 v[2:3], v[2:3], v[116:117]
	v_pk_mul_f32 v[6:7], v[6:7], v[118:119]
	v_cvt_pk_bf16_f32 v2, v2, v3
	v_cvt_pk_bf16_f32 v3, v6, v7
	global_store_dwordx2 v[136:137], v[2:3], off offset:192
	v_pk_mul_f32 v[2:3], v[22:23], v[134:135] op_sel_hi:[1,0]
	v_pk_mul_f32 v[6:7], v[24:25], v[134:135] op_sel_hi:[1,0]
	v_pk_mul_f32 v[2:3], v[2:3], v[120:121]
	v_pk_mul_f32 v[6:7], v[6:7], v[122:123]
	v_cvt_pk_bf16_f32 v2, v2, v3
	v_cvt_pk_bf16_f32 v3, v6, v7
	global_store_dwordx2 v[136:137], v[2:3], off offset:208
	v_pk_mul_f32 v[2:3], v[26:27], v[134:135] op_sel_hi:[1,0]
	v_pk_mul_f32 v[6:7], v[28:29], v[134:135] op_sel_hi:[1,0]
	v_pk_mul_f32 v[2:3], v[2:3], v[124:125]
	v_pk_mul_f32 v[6:7], v[6:7], v[126:127]
	v_cvt_pk_bf16_f32 v2, v2, v3
	v_cvt_pk_bf16_f32 v3, v6, v7
	global_store_dwordx2 v[136:137], v[2:3], off offset:224
	v_pk_mul_f32 v[2:3], v[30:31], v[134:135] op_sel_hi:[1,0]
	v_pk_mul_f32 v[6:7], v[32:33], v[134:135] op_sel_hi:[1,0]
	v_pk_mul_f32 v[58:59], v[58:59], v[96:97]
	v_pk_mul_f32 v[70:71], v[74:75], v[98:99]
	v_pk_mul_f32 v[2:3], v[2:3], v[128:129]
	v_pk_mul_f32 v[6:7], v[6:7], v[130:131]
	v_cvt_pk_bf16_f32 v16, v58, v59
	v_cvt_pk_bf16_f32 v17, v70, v71
	v_cvt_pk_bf16_f32 v2, v2, v3
	v_cvt_pk_bf16_f32 v3, v6, v7
	global_store_dwordx2 v[136:137], v[16:17], off offset:96
	global_store_dwordx2 v[136:137], v[2:3], off offset:240
	s_branch .LBB0_555
.Lattn_sg:
	v_lshlrev_b32_e32 v138, 2, v179
	global_load_dwordx4 v[140:143], v138, s[90:91]
	global_load_dwordx4 v[144:147], v138, s[90:91] offset:32
	global_load_dwordx4 v[160:163], v138, s[90:91] offset:64
	global_load_dwordx4 v[84:87], v138, s[90:91] offset:96
	global_load_dwordx4 v[88:91], v138, s[90:91] offset:128
	global_load_dwordx4 v[92:95], v138, s[90:91] offset:160
	global_load_dwordx4 v[96:99], v138, s[90:91] offset:192
	global_load_dwordx4 v[164:167], v138, s[90:91] offset:224
	global_load_dwordx4 v[100:103], v138, s[90:91] offset:256
	global_load_dwordx4 v[104:107], v138, s[90:91] offset:288
	global_load_dwordx4 v[108:111], v138, s[90:91] offset:320
	global_load_dwordx4 v[112:115], v138, s[90:91] offset:352
	global_load_dwordx4 v[116:119], v138, s[90:91] offset:384
	global_load_dwordx4 v[120:123], v138, s[90:91] offset:416
	global_load_dwordx4 v[124:127], v138, s[90:91] offset:448
	global_load_dwordx4 v[128:131], v138, s[90:91] offset:480
	s_branch .LBB0_585

; __device__ __forceinline__ void st8(bf16* p, f32x4 a, f32x4 b) { u32x4 w; w.x = cvtpk(a[0], a[1]); w.y = cvtpk(a[2], a[3]); w.z = cvtpk(b[0], b[1]); w.w = cvtpk(b[2], b[3]); *(u32x4*)p = w; }
; __device__ __forceinline__ f32x4 gelu4(f32x4 v) { return (f32x4){fgelu(v[0]), fgelu(v[1]), fgelu(v[2]), fgelu(v[3])}; }
; __device__ __forceinline__ float rot1(float v) { float r = __builtin_bit_cast(float, __builtin_amdgcn_update_dpp(0, __builtin_bit_cast(int, v), 0x121, 0xf, 0xf, false)); asm volatile("" : "+v"(r)); return r; }
; #define CP ((float*)(WSP() + WS_CP))
; #define BP ((float*)(WSP() + WS_BP))
;     __device__ __forceinline__ void operator()(const f32x4 (&acc)[2][2][4][2], const pg8::Unit& u, int wr, int wc, int fr, int fq) const {
;     ...
;             for (int n = 0; n < 2; ++n) {
; #pragma unroll
;                 for (int m = 0; m < 4; ++m) x[m][n] = acc[ai][0][m][n] * rs[ai][m];
;                 f32x4 t2 = (f32x4){0.f, 0.f, 0.f, 0.f}, t3 = t2;
;                 if (band > 0 && fr == 15) { t2 = T[((((band - 1) * 4 + wc) * 2 + n) * 4 + fq) * 2 + 0]; t3 = T[((((band - 1) * 4 + wc) * 2 + n) * 4 + fq) * 2 + 1]; }
; #pragma unroll
;                 for (int j = 0; j < 4; ++j) {
;                     const float y2 = fr == 15 ? t2[j] : x[2][n][j], y3 = fr == 15 ? t3[j] : x[3][n][j];
;                     L2[n][j] = rot1(y2); L3[n][j] = rot1(y3);
;                 }
;             }
; #pragma unroll
;             for (int m = 0; m < 4; ++m) {
;                 const int row = u.pm * 256 + ai * 128 + wr * 64 + 4 * fr + m;
;                 f32x4 o[2], bo[2];
; #pragma unroll
;                 for (int n = 0; n < 2; ++n) {
;                     const f32x4 p1 = m == 0 ? L3[n] : x[m - 1][n];
;                     const f32x4 p2 = m == 0 ? L2[n] : (m == 1 ? L3[n] : x[m - 2][n]);
;                     bo[n] = acc[ai][1][m][n] * rs[ai][m];
;                     o[n] = bv[n] + w2[n] * x[m][n] + w1[n] * p1 + w0[n] * p2;
;                 }
;                 if (band == 0 && fr == 0 && m < 2) {
;                     float* cp = CP + (size_t)(u.pm * 2 + m) * DFF + hid; float* bp = BP + (size_t)(u.pm * 2 + m) * DFF + hid;
;                     *(f32x4*)cp = o[0]; *(f32x4*)(cp + 4) = o[1]; *(f32x4*)bp = bo[0]; *(f32x4*)(bp + 4) = bo[1];
;                 } else {
;                     st8(ACT + (size_t)row * DFF + hid, gelu4(o[0]) * bo[0], gelu4(o[1]) * bo[1]);
.LBB0_1201:
	s_or_b64 exec, exec, s[56:57]
	s_waitcnt lgkmcnt(1)
	v_cndmask_b32_e64 v145, v162, v174, s[6:7]
	v_cndmask_b32_e64 v115, v165, v177, s[6:7]
	v_cndmask_b32_e64 v150, v164, v176, s[6:7]
	v_cndmask_b32_e64 v151, v163, v175, s[6:7]
	s_waitcnt lgkmcnt(0)
	v_cndmask_b32_e64 v168, v143, v181, s[6:7]
	v_cndmask_b32_e64 v169, v142, v180, s[6:7]
	v_cndmask_b32_e64 v173, v141, v179, s[6:7]
	v_cndmask_b32_e64 v174, v140, v178, s[6:7]
	v_mov_b32_dpp v144, v145 row_ror:1 row_mask:0xf bank_mask:0xf
	s_nop 0
	v_mov_b32_dpp v212, v174 row_ror:1 row_mask:0xf bank_mask:0xf
	v_mov_b32_dpp v145, v151 row_ror:1 row_mask:0xf bank_mask:0xf
	v_mov_b32_dpp v213, v173 row_ror:1 row_mask:0xf bank_mask:0xf
	v_mov_b32_dpp v216, v150 row_ror:1 row_mask:0xf bank_mask:0xf
	v_mov_b32_dpp v214, v169 row_ror:1 row_mask:0xf bank_mask:0xf
	v_mov_b32_dpp v217, v115 row_ror:1 row_mask:0xf bank_mask:0xf
	v_mov_b32_dpp v215, v168 row_ror:1 row_mask:0xf bank_mask:0xf
	v_mov_b32_e32 v173, 0
	v_mov_b32_e32 v174, 0
	v_mov_b32_e32 v175, 0
	v_mov_b32_e32 v176, 0
	v_mov_b32_e32 v177, 0
	v_mov_b32_e32 v178, 0
	v_mov_b32_e32 v179, 0
	s_and_saveexec_b64 s[56:57], s[30:31]
	s_cbranch_execz .LBB0_1203
	v_add_u32_e32 v115, 0x20480, v228
	ds_read_b128 v[172:175], v115
	ds_read_b128 v[176:179], v115 offset:16
.LBB0_1203:
	s_or_b64 exec, exec, s[56:57]
	v_fmamk_f32 v115, v170, 0x3a800000, v227
	v_rsq_f32_e32 v170, v115
	v_mov_b32_e32 v150, v210
	v_mov_b32_e32 v151, v210
	v_pk_mul_f32 v[168:169], v[152:153], v[150:151]
	v_mov_b32_e32 v150, v208
	v_mov_b32_e32 v151, v208
	v_pk_mul_f32 v[180:181], v[158:159], v[170:171] op_sel_hi:[1,0]
	v_pk_mul_f32 v[150:151], v[146:147], v[150:151]
	v_pk_mul_f32 v[158:159], v[154:155], v[170:171] op_sel_hi:[1,0]
	s_waitcnt lgkmcnt(1)
	v_cndmask_b32_e64 v147, v167, v173, s[6:7]
	v_cndmask_b32_e64 v153, v166, v172, s[6:7]
	s_waitcnt lgkmcnt(0)
	v_cndmask_b32_e64 v173, v148, v176, s[6:7]
	v_cndmask_b32_e64 v146, v168, v174, s[6:7]
	v_cndmask_b32_e64 v155, v150, v178, s[6:7]
	v_cndmask_b32_e64 v154, v149, v177, s[6:7]
	v_mov_b32_dpp v172, v173 row_ror:1 row_mask:0xf bank_mask:0xf
	v_pk_fma_f32 v[176:177], v[76:77], v[158:159], v[80:81]
	v_pk_mul_f32 v[160:161], v[160:161], v[170:171] op_sel_hi:[1,0]
	v_pk_mul_f32 v[156:157], v[156:157], v[170:171] op_sel_hi:[1,0]
	v_cndmask_b32_e64 v115, v169, v175, s[6:7]
	v_cndmask_b32_e64 v179, v151, v179, s[6:7]
	v_mov_b32_dpp v152, v153 row_ror:1 row_mask:0xf bank_mask:0xf
	v_mov_b32_dpp v173, v154 row_ror:1 row_mask:0xf bank_mask:0xf
	v_mov_b32_dpp v174, v155 row_ror:1 row_mask:0xf bank_mask:0xf
	v_pk_fma_f32 v[176:177], v[64:65], v[212:213], v[176:177]
	v_mov_b32_dpp v153, v147 row_ror:1 row_mask:0xf bank_mask:0xf
	v_mov_b32_dpp v154, v146 row_ror:1 row_mask:0xf bank_mask:0xf
	v_mov_b32_dpp v155, v115 row_ror:1 row_mask:0xf bank_mask:0xf
	v_mov_b32_dpp v175, v179 row_ror:1 row_mask:0xf bank_mask:0xf
	v_pk_fma_f32 v[146:147], v[78:79], v[156:157], v[82:83]
	v_pk_fma_f32 v[144:145], v[60:61], v[144:145], v[176:177]
	v_pk_fma_f32 v[176:177], v[90:91], v[160:161], v[94:95]
	v_pk_fma_f32 v[178:179], v[88:89], v[180:181], v[92:93]
	v_pk_fma_f32 v[146:147], v[66:67], v[214:215], v[146:147]
	v_pk_fma_f32 v[178:179], v[84:85], v[172:173], v[178:179]
	v_pk_fma_f32 v[176:177], v[86:87], v[174:175], v[176:177]
	v_pk_mul_f32 v[138:139], v[138:139], v[170:171] op_sel_hi:[1,0]
	v_pk_mul_f32 v[136:137], v[136:137], v[170:171] op_sel_hi:[1,0]
	v_pk_fma_f32 v[146:147], v[62:63], v[216:217], v[146:147]
	v_pk_mul_f32 v[134:135], v[134:135], v[170:171] op_sel_hi:[1,0]
	v_pk_mul_f32 v[132:133], v[132:133], v[170:171] op_sel_hi:[1,0]
	v_pk_fma_f32 v[154:155], v[74:75], v[154:155], v[176:177]
	v_pk_fma_f32 v[152:153], v[72:73], v[152:153], v[178:179]
	s_and_saveexec_b64 s[38:39], s[8:9]
	s_xor_b64 s[56:57], exec, s[38:39]
	s_cbranch_execz .LBB0_1205
	v_mul_f32_e32 v115, 0x3dd2d3e8, v144
	v_fma_f32 v115, -v144, v115, s95
	v_mul_f32_e32 v170, 0x3dd2d3e8, v145
	v_mul_f32_e32 v115, v144, v115
	v_fma_f32 v170, -v145, v170, s95
	v_exp_f32_e32 v115, v115
	v_mul_f32_e32 v170, v145, v170
	v_exp_f32_e32 v170, v170
	v_mul_f32_e32 v179, 0x3dd2d3e8, v147
	v_add_f32_e32 v115, 1.0, v115
	v_rcp_f32_e32 v178, v115
	v_add_f32_e32 v115, 1.0, v170
	v_mul_f32_e32 v170, 0x3dd2d3e8, v146
	v_fma_f32 v170, -v146, v170, s95
	v_mul_f32_e32 v170, v146, v170
	v_fma_f32 v179, -v147, v179, s95
	v_exp_f32_e32 v170, v170
	v_mul_f32_e32 v179, v147, v179
	v_exp_f32_e32 v201, v179
	v_rcp_f32_e32 v179, v115
	v_add_f32_e32 v115, 1.0, v170
	v_rcp_f32_e32 v216, v115
	v_add_f32_e32 v115, 1.0, v201
	v_rcp_f32_e32 v217, v115
	v_mul_f32_e32 v115, 0x3dd2d3e8, v152
	v_fma_f32 v115, -v152, v115, s95
	v_mul_f32_e32 v170, 0x3dd2d3e8, v153
	v_mul_f32_e32 v115, v152, v115
	v_fma_f32 v170, -v153, v170, s95
	v_exp_f32_e32 v115, v115
	v_mul_f32_e32 v170, v153, v170
	v_exp_f32_e32 v170, v170
	v_pk_mul_f32 v[144:145], v[144:145], v[178:179]
	v_add_f32_e32 v115, 1.0, v115
	v_rcp_f32_e32 v178, v115
	v_add_f32_e32 v115, 1.0, v170
	v_mul_f32_e32 v170, 0x3dd2d3e8, v154
	v_fma_f32 v170, -v154, v170, s95
	v_mul_f32_e32 v179, 0x3dd2d3e8, v155
	v_mul_f32_e32 v170, v154, v170
	v_fma_f32 v179, -v155, v179, s95
	v_exp_f32_e32 v170, v170
	v_mul_f32_e32 v179, v155, v179
	v_exp_f32_e32 v201, v179
	v_rcp_f32_e32 v179, v115
	v_add_f32_e32 v115, 1.0, v170
	v_pk_mul_f32 v[146:147], v[146:147], v[216:217]
	v_rcp_f32_e32 v216, v115
	v_add_f32_e32 v115, 1.0, v201
	v_rcp_f32_e32 v217, v115
	v_mov_b64_e32 v[176:177], s[24:25]
	v_pk_mul_f32 v[138:139], v[138:139], v[146:147]
	v_pk_mul_f32 v[136:137], v[136:137], v[144:145]
	v_pk_mul_f32 v[144:145], v[152:153], v[178:179]
	v_pk_mul_f32 v[146:147], v[154:155], v[216:217]
	v_mad_i64_i32 v[176:177], s[38:39], v200, s94, v[176:177]
	v_pk_mul_f32 v[146:147], v[134:135], v[146:147]
	v_pk_mul_f32 v[134:135], v[132:133], v[144:145]
	v_lshl_add_u64 v[176:177], v[198:199], 1, v[176:177]
	v_cvt_pk_bf16_f32 v132, v136, v137
	v_cvt_pk_bf16_f32 v133, v138, v139
	v_cvt_pk_bf16_f32 v134, v134, v135
	v_cvt_pk_bf16_f32 v135, v146, v147
	global_store_dwordx4 v[176:177], v[132:135], off

; __device__ __forceinline__ void st8(bf16* p, f32x4 a, f32x4 b) { u32x4 w; w.x = cvtpk(a[0], a[1]); w.y = cvtpk(a[2], a[3]); w.z = cvtpk(b[0], b[1]); w.w = cvtpk(b[2], b[3]); *(u32x4*)p = w; }
; __device__ __forceinline__ f32x4 gelu4(f32x4 v) { return (f32x4){fgelu(v[0]), fgelu(v[1]), fgelu(v[2]), fgelu(v[3])}; }
; __device__ __forceinline__ float rot1(float v) { float r = __builtin_bit_cast(float, __builtin_amdgcn_update_dpp(0, __builtin_bit_cast(int, v), 0x121, 0xf, 0xf, false)); asm volatile("" : "+v"(r)); return r; }
; #define CP ((float*)(WSP() + WS_CP))
; #define BP ((float*)(WSP() + WS_BP))
;     __device__ __forceinline__ void operator()(const f32x4 (&acc)[2][2][4][2], const pg8::Unit& u, int wr, int wc, int fr, int fq) const {
;     ...
;             for (int n = 0; n < 2; ++n) {
; #pragma unroll
;                 for (int m = 0; m < 4; ++m) x[m][n] = acc[ai][0][m][n] * rs[ai][m];
;                 f32x4 t2 = (f32x4){0.f, 0.f, 0.f, 0.f}, t3 = t2;
;                 if (band > 0 && fr == 15) { t2 = T[((((band - 1) * 4 + wc) * 2 + n) * 4 + fq) * 2 + 0]; t3 = T[((((band - 1) * 4 + wc) * 2 + n) * 4 + fq) * 2 + 1]; }
; #pragma unroll
;                 for (int j = 0; j < 4; ++j) {
;                     const float y2 = fr == 15 ? t2[j] : x[2][n][j], y3 = fr == 15 ? t3[j] : x[3][n][j];
;                     L2[n][j] = rot1(y2); L3[n][j] = rot1(y3);
;                 }
;             }
; #pragma unroll
;             for (int m = 0; m < 4; ++m) {
;                 const int row = u.pm * 256 + ai * 128 + wr * 64 + 4 * fr + m;
;                 f32x4 o[2], bo[2];
; #pragma unroll
;                 for (int n = 0; n < 2; ++n) {
;                     const f32x4 p1 = m == 0 ? L3[n] : x[m - 1][n];
;                     const f32x4 p2 = m == 0 ? L2[n] : (m == 1 ? L3[n] : x[m - 2][n]);
;                     bo[n] = acc[ai][1][m][n] * rs[ai][m];
;                     o[n] = bv[n] + w2[n] * x[m][n] + w1[n] * p1 + w0[n] * p2;
;                 }
;                 if (band == 0 && fr == 0 && m < 2) {
;                     float* cp = CP + (size_t)(u.pm * 2 + m) * DFF + hid; float* bp = BP + (size_t)(u.pm * 2 + m) * DFF + hid;
;                     *(f32x4*)cp = o[0]; *(f32x4*)(cp + 4) = o[1]; *(f32x4*)bp = bo[0]; *(f32x4*)(bp + 4) = bo[1];
;                 } else {
;                     st8(ACT + (size_t)row * DFF + hid, gelu4(o[0]) * bo[0], gelu4(o[1]) * bo[1]);
.LBB0_1217:
	s_or_b64 exec, exec, s[54:55]
	v_pk_mul_f32 v[70:71], v[70:71], v[202:203] op_sel_hi:[1,0]
	v_pk_mul_f32 v[68:69], v[68:69], v[202:203] op_sel_hi:[1,0]
	v_pk_mul_f32 v[58:59], v[58:59], v[114:115] op_sel_hi:[1,0]
	v_pk_mul_f32 v[56:57], v[56:57], v[114:115] op_sel_hi:[1,0]
	s_waitcnt lgkmcnt(1)
	v_cndmask_b32_e64 v97, v71, v101, s[6:7]
	v_cndmask_b32_e64 v100, v70, v100, s[6:7]
	v_cndmask_b32_e64 v99, v69, v99, s[6:7]
	v_cndmask_b32_e64 v98, v68, v98, s[6:7]
	s_waitcnt lgkmcnt(0)
	v_cndmask_b32_e64 v101, v59, v105, s[6:7]
	v_cndmask_b32_e64 v104, v58, v104, s[6:7]
	v_cndmask_b32_e64 v103, v57, v103, s[6:7]
	v_cndmask_b32_e64 v102, v56, v102, s[6:7]
	v_mov_b32_dpp v120, v98 row_ror:1 row_mask:0xf bank_mask:0xf
	s_nop 0
	v_mov_b32_dpp v116, v102 row_ror:1 row_mask:0xf bank_mask:0xf
	v_mov_b32_dpp v121, v99 row_ror:1 row_mask:0xf bank_mask:0xf
	v_mov_b32_dpp v117, v103 row_ror:1 row_mask:0xf bank_mask:0xf
	v_mov_b32_dpp v122, v100 row_ror:1 row_mask:0xf bank_mask:0xf
	v_mov_b32_dpp v118, v104 row_ror:1 row_mask:0xf bank_mask:0xf
	v_mov_b32_dpp v123, v97 row_ror:1 row_mask:0xf bank_mask:0xf
	v_mov_b32_dpp v119, v101 row_ror:1 row_mask:0xf bank_mask:0xf
	v_mov_b32_e32 v97, 0
	v_mov_b32_e32 v98, 0
	v_mov_b32_e32 v99, 0
	v_mov_b32_e32 v100, 0
	v_mov_b32_e32 v101, 0
	v_mov_b32_e32 v102, 0
	v_mov_b32_e32 v103, 0
	s_and_saveexec_b64 s[54:55], s[36:37]
	s_cbranch_execz .LBB0_1219
	v_add_u32_e32 v100, 0x20480, v229
	ds_read_b128 v[96:99], v100
	ds_read_b128 v[100:103], v100 offset:16
.LBB0_1219:
	s_or_b64 exec, exec, s[54:55]
	v_fmamk_f32 v104, v112, 0x3a800000, v227
	v_rsq_f32_e32 v112, v104
	v_mov_b32_e32 v203, v202
	v_mov_b32_e32 v115, v114
	v_pk_mul_f32 v[44:45], v[44:45], v[202:203]
	v_pk_mul_f32 v[110:111], v[52:53], v[112:113] op_sel_hi:[1,0]
	v_mov_b32_e32 v52, v202
	v_mov_b32_e32 v53, v202
	v_pk_mul_f32 v[46:47], v[46:47], v[52:53]
	v_mov_b32_e32 v52, v114
	v_mov_b32_e32 v53, v114
	v_pk_mul_f32 v[42:43], v[42:43], v[52:53]
	v_pk_mul_f32 v[40:41], v[40:41], v[114:115]
	v_pk_mul_f32 v[108:109], v[54:55], v[112:113] op_sel_hi:[1,0]
	v_pk_mul_f32 v[104:105], v[50:51], v[112:113] op_sel_hi:[1,0]
	v_pk_mul_f32 v[106:107], v[48:49], v[112:113] op_sel_hi:[1,0]
	s_waitcnt lgkmcnt(1)
	v_cndmask_b32_e64 v49, v46, v98, s[6:7]
	v_cndmask_b32_e64 v50, v45, v97, s[6:7]
	v_cndmask_b32_e64 v51, v44, v96, s[6:7]
	s_waitcnt lgkmcnt(0)
	v_cndmask_b32_e64 v55, v42, v102, s[6:7]
	v_cndmask_b32_e64 v54, v41, v101, s[6:7]
	v_cndmask_b32_e64 v53, v40, v100, s[6:7]
	v_cndmask_b32_e64 v48, v47, v99, s[6:7]
	s_nop 0
	v_mov_b32_dpp v96, v53 row_ror:1 row_mask:0xf bank_mask:0xf
	v_mov_b32_dpp v97, v54 row_ror:1 row_mask:0xf bank_mask:0xf
	v_mov_b32_dpp v98, v55 row_ror:1 row_mask:0xf bank_mask:0xf
	v_mov_b32_dpp v52, v51 row_ror:1 row_mask:0xf bank_mask:0xf
	v_mov_b32_dpp v53, v50 row_ror:1 row_mask:0xf bank_mask:0xf
	v_mov_b32_dpp v54, v49 row_ror:1 row_mask:0xf bank_mask:0xf
	v_mov_b32_dpp v55, v48 row_ror:1 row_mask:0xf bank_mask:0xf
	v_pk_fma_f32 v[48:49], v[78:79], v[104:105], v[82:83]
	v_pk_fma_f32 v[50:51], v[76:77], v[106:107], v[80:81]
	v_cndmask_b32_e64 v103, v43, v103, s[6:7]
	v_pk_fma_f32 v[100:101], v[64:65], v[116:117], v[50:51]
	v_pk_fma_f32 v[48:49], v[66:67], v[118:119], v[48:49]
	v_mov_b32_dpp v99, v103 row_ror:1 row_mask:0xf bank_mask:0xf
	v_pk_fma_f32 v[50:51], v[62:63], v[122:123], v[48:49]
	v_pk_fma_f32 v[48:49], v[60:61], v[120:121], v[100:101]
	v_pk_fma_f32 v[100:101], v[90:91], v[108:109], v[94:95]
	v_pk_fma_f32 v[102:103], v[88:89], v[110:111], v[92:93]
	v_pk_mul_f32 v[38:39], v[38:39], v[112:113] op_sel_hi:[1,0]
	v_pk_fma_f32 v[102:103], v[84:85], v[96:97], v[102:103]
	v_pk_fma_f32 v[100:101], v[86:87], v[98:99], v[100:101]
	v_pk_mul_f32 v[36:37], v[36:37], v[112:113] op_sel_hi:[1,0]
	v_pk_mul_f32 v[34:35], v[34:35], v[112:113] op_sel_hi:[1,0]
	v_pk_mul_f32 v[32:33], v[32:33], v[112:113] op_sel_hi:[1,0]
	v_pk_fma_f32 v[54:55], v[74:75], v[54:55], v[100:101]
	v_pk_fma_f32 v[52:53], v[72:73], v[52:53], v[102:103]
	s_and_saveexec_b64 s[54:55], s[10:11]
	s_xor_b64 s[54:55], exec, s[54:55]
	s_cbranch_execz .LBB0_1221
	v_mul_f32_e32 v112, 0x3dd2d3e8, v50
	v_mul_f32_e32 v102, 0x3dd2d3e8, v48
	v_mul_f32_e32 v103, 0x3dd2d3e8, v49
	v_fma_f32 v112, -v50, v112, s95
	v_mul_f32_e32 v120, 0x3dd2d3e8, v51
	v_fma_f32 v102, -v48, v102, s95
	v_fma_f32 v103, -v49, v103, s95
	v_mul_f32_e32 v112, v50, v112
	v_fma_f32 v120, -v51, v120, s95
	v_mul_f32_e32 v102, v48, v102
	v_mul_f32_e32 v103, v49, v103
	v_exp_f32_e32 v112, v112
	v_mul_f32_e32 v120, v51, v120
	v_exp_f32_e32 v102, v102
	v_exp_f32_e32 v103, v103
	v_exp_f32_e32 v121, v120
	v_add_f32_e32 v112, 1.0, v112
	v_add_f32_e32 v102, 1.0, v102
	v_add_f32_e32 v103, 1.0, v103
	v_rcp_f32_e32 v120, v112
	v_add_f32_e32 v112, 1.0, v121
	v_rcp_f32_e32 v102, v102
	v_rcp_f32_e32 v103, v103
	v_rcp_f32_e32 v121, v112
	v_mul_f32_e32 v112, 0x3dd2d3e8, v54
	v_fma_f32 v112, -v54, v112, s95
	v_pk_mul_f32 v[48:49], v[48:49], v[102:103]
	v_mul_f32_e32 v102, 0x3dd2d3e8, v52
	v_mul_f32_e32 v103, 0x3dd2d3e8, v53
	v_pk_mul_f32 v[50:51], v[50:51], v[120:121]
	v_mul_f32_e32 v120, 0x3dd2d3e8, v55
	v_fma_f32 v102, -v52, v102, s95
	v_fma_f32 v103, -v53, v103, s95
	v_mul_f32_e32 v112, v54, v112
	v_fma_f32 v120, -v55, v120, s95
	v_mul_f32_e32 v102, v52, v102
	v_mul_f32_e32 v103, v53, v103
	v_exp_f32_e32 v112, v112
	v_mul_f32_e32 v120, v55, v120
	v_exp_f32_e32 v102, v102
	v_exp_f32_e32 v103, v103
	v_exp_f32_e32 v121, v120
	v_add_f32_e32 v112, 1.0, v112
	v_add_f32_e32 v102, 1.0, v102
	v_add_f32_e32 v103, 1.0, v103
	v_rcp_f32_e32 v120, v112
	v_add_f32_e32 v112, 1.0, v121
	v_rcp_f32_e32 v102, v102
	v_rcp_f32_e32 v103, v103
	v_rcp_f32_e32 v121, v112
	v_mov_b64_e32 v[100:101], s[24:25]
	v_pk_mul_f32 v[38:39], v[38:39], v[50:51]
	v_pk_mul_f32 v[36:37], v[36:37], v[48:49]
	v_pk_mul_f32 v[48:49], v[52:53], v[102:103]
	v_pk_mul_f32 v[50:51], v[54:55], v[120:121]
	v_mad_i64_i32 v[100:101], s[56:57], v206, s94, v[100:101]
	v_pk_mul_f32 v[50:51], v[34:35], v[50:51]
	v_pk_mul_f32 v[34:35], v[32:33], v[48:49]
	v_lshl_add_u64 v[100:101], v[198:199], 1, v[100:101]
	v_cvt_pk_bf16_f32 v32, v36, v37
	v_cvt_pk_bf16_f32 v33, v38, v39
	v_cvt_pk_bf16_f32 v34, v34, v35
	v_cvt_pk_bf16_f32 v35, v50, v51
	global_store_dwordx4 v[100:101], v[32:35], off
